# E22: G1-even epilogue loads the 4 lower-bound vectors once per tile (+E21 deferred conv scale multiplies, E18 setup GEMV, E17 norm gamma hoist)
# speedup vs baseline: 1.0043x; 1.0014x over previous
; __device__ __forceinline__ void conv_matrix(const float* __restrict__ src, int K, int N, int Npad, bf16_t* __restrict__ dst, const float* __restrict__ scale, float* tile) {
;     ...
; #pragma unroll
;     for (int i = 0; i < 8; ++i) { const int k = k0a + ty + 8 * i, n = n0a + tx; float v = (n < N) ? src[(size_t)k * N + n] : 0.f; if (scale) v *= scale[k]; va[i] = v; }
.LBB0_213:
	s_or_b64 exec, exec, s[6:7]
	v_cndmask_b32_e64 v11, 0, 1, s[18:19]
	v_cmp_ne_u32_e64 s[6:7], 1, v11
	s_andn2_b64 vcc, exec, s[18:19]
	v_ashrrev_i32_e32 v11, 31, v10
	s_cbranch_vccnz .LBB0_215
	v_lshl_add_u64 v[22:23], v[10:11], 2, s[16:17]
	global_load_dword v214, v[22:23], off

; __device__ __forceinline__ void conv_matrix(const float* __restrict__ src, int K, int N, int Npad, bf16_t* __restrict__ dst, const float* __restrict__ scale, float* tile) {
;     ...
; #pragma unroll
;     for (int i = 0; i < 8; ++i) { const int k = k0a + ty + 8 * i, n = n0a + tx; float v = (n < N) ? src[(size_t)k * N + n] : 0.f; if (scale) v *= scale[k]; va[i] = v; }
.LBB0_217:
	s_or_b64 exec, exec, s[24:25]
	s_and_b64 vcc, exec, s[6:7]
	s_cbranch_vccnz .LBB0_219
	v_lshl_add_u64 v[22:23], v[10:11], 2, s[16:17]
	global_load_dword v215, v[22:23], off offset:32

; __device__ __forceinline__ void conv_matrix(const float* __restrict__ src, int K, int N, int Npad, bf16_t* __restrict__ dst, const float* __restrict__ scale, float* tile) {
;     ...
; #pragma unroll
;     for (int i = 0; i < 8; ++i) { const int k = k0a + ty + 8 * i, n = n0a + tx; float v = (n < N) ? src[(size_t)k * N + n] : 0.f; if (scale) v *= scale[k]; va[i] = v; }
.LBB0_221:
	s_or_b64 exec, exec, s[24:25]
	s_and_b64 vcc, exec, s[6:7]
	s_cbranch_vccnz .LBB0_223
	v_lshl_add_u64 v[24:25], v[10:11], 2, s[16:17]
	global_load_dword v216, v[24:25], off offset:64

; __device__ __forceinline__ void conv_matrix(const float* __restrict__ src, int K, int N, int Npad, bf16_t* __restrict__ dst, const float* __restrict__ scale, float* tile) {
;     ...
; #pragma unroll
;     for (int i = 0; i < 8; ++i) { const int k = k0a + ty + 8 * i, n = n0a + tx; float v = (n < N) ? src[(size_t)k * N + n] : 0.f; if (scale) v *= scale[k]; va[i] = v; }
.LBB0_225:
	s_or_b64 exec, exec, s[24:25]
	s_and_b64 vcc, exec, s[6:7]
	s_cbranch_vccnz .LBB0_227
	v_lshl_add_u64 v[24:25], v[10:11], 2, s[16:17]
	global_load_dword v217, v[24:25], off offset:96

; __device__ __forceinline__ void conv_matrix(const float* __restrict__ src, int K, int N, int Npad, bf16_t* __restrict__ dst, const float* __restrict__ scale, float* tile) {
;     ...
; #pragma unroll
;     for (int i = 0; i < 8; ++i) { const int k = k0a + ty + 8 * i, n = n0a + tx; float v = (n < N) ? src[(size_t)k * N + n] : 0.f; if (scale) v *= scale[k]; va[i] = v; }
.LBB0_229:
	s_or_b64 exec, exec, s[24:25]
	s_and_b64 vcc, exec, s[6:7]
	s_cbranch_vccnz .LBB0_231
	v_lshl_add_u64 v[26:27], v[10:11], 2, s[16:17]
	global_load_dword v218, v[26:27], off offset:128

; __device__ __forceinline__ void conv_matrix(const float* __restrict__ src, int K, int N, int Npad, bf16_t* __restrict__ dst, const float* __restrict__ scale, float* tile) {
;     ...
; #pragma unroll
;     for (int i = 0; i < 8; ++i) { const int k = k0a + ty + 8 * i, n = n0a + tx; float v = (n < N) ? src[(size_t)k * N + n] : 0.f; if (scale) v *= scale[k]; va[i] = v; }
.LBB0_233:
	s_or_b64 exec, exec, s[24:25]
	s_and_b64 vcc, exec, s[6:7]
	s_cbranch_vccnz .LBB0_235
	v_lshl_add_u64 v[26:27], v[10:11], 2, s[16:17]
	global_load_dword v219, v[26:27], off offset:160

; __device__ __forceinline__ void conv_matrix(const float* __restrict__ src, int K, int N, int Npad, bf16_t* __restrict__ dst, const float* __restrict__ scale, float* tile) {
;     ...
; #pragma unroll
;     for (int i = 0; i < 8; ++i) { const int k = k0a + ty + 8 * i, n = n0a + tx; float v = (n < N) ? src[(size_t)k * N + n] : 0.f; if (scale) v *= scale[k]; va[i] = v; }
.LBB0_237:
	s_or_b64 exec, exec, s[24:25]
	s_and_b64 vcc, exec, s[6:7]
	s_cbranch_vccnz .LBB0_239
	v_lshl_add_u64 v[28:29], v[10:11], 2, s[16:17]
	global_load_dword v220, v[28:29], off offset:192

; __device__ __forceinline__ void conv_matrix(const float* __restrict__ src, int K, int N, int Npad, bf16_t* __restrict__ dst, const float* __restrict__ scale, float* tile) {
;     ...
; #pragma unroll
;     for (int i = 0; i < 8; ++i) { const int k = k0a + ty + 8 * i, n = n0a + tx; float v = (n < N) ? src[(size_t)k * N + n] : 0.f; if (scale) v *= scale[k]; va[i] = v; }
.LBB0_241:
	s_or_b64 exec, exec, s[24:25]
	s_and_b64 vcc, exec, s[6:7]
	s_cbranch_vccnz .LBB0_243
	v_lshl_add_u64 v[10:11], v[10:11], 2, s[16:17]
	global_load_dword v221, v[10:11], off offset:224

; __device__ __forceinline__ void conv_matrix(const float* __restrict__ src, int K, int N, int Npad, bf16_t* __restrict__ dst, const float* __restrict__ scale, float* tile) {
;     ...
; #pragma unroll
;       for (int i = 0; i < 8; ++i) { const int k = k0b + ty + 8 * i, n = n0b + tx; float v = (n < N) ? src[(size_t)k * N + n] : 0.f; if (scale) v *= scale[k]; vb[i] = v; }
.LBB0_246:
	s_or_b64 exec, exec, s[24:25]
	s_and_b64 vcc, exec, s[6:7]
	v_ashrrev_i32_e32 v11, 31, v10
	s_cbranch_vccnz .LBB0_248
	v_lshl_add_u64 v[2:3], v[10:11], 2, s[16:17]
	global_load_dword v222, v[2:3], off

; __device__ __forceinline__ void conv_matrix(const float* __restrict__ src, int K, int N, int Npad, bf16_t* __restrict__ dst, const float* __restrict__ scale, float* tile) {
;     ...
; #pragma unroll
;       for (int i = 0; i < 8; ++i) { const int k = k0b + ty + 8 * i, n = n0b + tx; float v = (n < N) ? src[(size_t)k * N + n] : 0.f; if (scale) v *= scale[k]; vb[i] = v; }
.LBB0_250:
	s_or_b64 exec, exec, s[24:25]
	s_and_b64 vcc, exec, s[6:7]
	s_cbranch_vccnz .LBB0_252
	v_lshl_add_u64 v[2:3], v[10:11], 2, s[16:17]
	global_load_dword v223, v[2:3], off offset:32

; __device__ __forceinline__ void conv_matrix(const float* __restrict__ src, int K, int N, int Npad, bf16_t* __restrict__ dst, const float* __restrict__ scale, float* tile) {
;     ...
; #pragma unroll
;       for (int i = 0; i < 8; ++i) { const int k = k0b + ty + 8 * i, n = n0b + tx; float v = (n < N) ? src[(size_t)k * N + n] : 0.f; if (scale) v *= scale[k]; vb[i] = v; }
.LBB0_254:
	s_or_b64 exec, exec, s[24:25]
	s_and_b64 vcc, exec, s[6:7]
	s_cbranch_vccnz .LBB0_256
	v_lshl_add_u64 v[4:5], v[10:11], 2, s[16:17]
	global_load_dword v224, v[4:5], off offset:64

; __device__ __forceinline__ void conv_matrix(const float* __restrict__ src, int K, int N, int Npad, bf16_t* __restrict__ dst, const float* __restrict__ scale, float* tile) {
;     ...
; #pragma unroll
;       for (int i = 0; i < 8; ++i) { const int k = k0b + ty + 8 * i, n = n0b + tx; float v = (n < N) ? src[(size_t)k * N + n] : 0.f; if (scale) v *= scale[k]; vb[i] = v; }
.LBB0_258:
	s_or_b64 exec, exec, s[24:25]
	s_and_b64 vcc, exec, s[6:7]
	s_cbranch_vccnz .LBB0_260
	v_lshl_add_u64 v[4:5], v[10:11], 2, s[16:17]
	global_load_dword v225, v[4:5], off offset:96

; __device__ __forceinline__ void conv_matrix(const float* __restrict__ src, int K, int N, int Npad, bf16_t* __restrict__ dst, const float* __restrict__ scale, float* tile) {
;     ...
; #pragma unroll
;       for (int i = 0; i < 8; ++i) { const int k = k0b + ty + 8 * i, n = n0b + tx; float v = (n < N) ? src[(size_t)k * N + n] : 0.f; if (scale) v *= scale[k]; vb[i] = v; }
.LBB0_262:
	s_or_b64 exec, exec, s[24:25]
	s_and_b64 vcc, exec, s[6:7]
	s_cbranch_vccnz .LBB0_264
	v_lshl_add_u64 v[6:7], v[10:11], 2, s[16:17]
	global_load_dword v226, v[6:7], off offset:128

; __device__ __forceinline__ void conv_matrix(const float* __restrict__ src, int K, int N, int Npad, bf16_t* __restrict__ dst, const float* __restrict__ scale, float* tile) {
;     ...
; #pragma unroll
;       for (int i = 0; i < 8; ++i) { const int k = k0b + ty + 8 * i, n = n0b + tx; float v = (n < N) ? src[(size_t)k * N + n] : 0.f; if (scale) v *= scale[k]; vb[i] = v; }
.LBB0_266:
	s_or_b64 exec, exec, s[24:25]
	s_and_b64 vcc, exec, s[6:7]
	s_cbranch_vccnz .LBB0_268
	v_lshl_add_u64 v[6:7], v[10:11], 2, s[16:17]
	global_load_dword v227, v[6:7], off offset:160

; __device__ __forceinline__ void conv_matrix(const float* __restrict__ src, int K, int N, int Npad, bf16_t* __restrict__ dst, const float* __restrict__ scale, float* tile) {
;     ...
; #pragma unroll
;       for (int i = 0; i < 8; ++i) { const int k = k0b + ty + 8 * i, n = n0b + tx; float v = (n < N) ? src[(size_t)k * N + n] : 0.f; if (scale) v *= scale[k]; vb[i] = v; }
.LBB0_270:
	s_or_b64 exec, exec, s[24:25]
	s_and_b64 vcc, exec, s[6:7]
	s_cbranch_vccnz .LBB0_272
	v_lshl_add_u64 v[28:29], v[10:11], 2, s[16:17]
	global_load_dword v228, v[28:29], off offset:192

; __device__ __forceinline__ void conv_matrix(const float* __restrict__ src, int K, int N, int Npad, bf16_t* __restrict__ dst, const float* __restrict__ scale, float* tile) {
;     ...
; #pragma unroll
;       for (int i = 0; i < 8; ++i) { const int k = k0b + ty + 8 * i, n = n0b + tx; float v = (n < N) ? src[(size_t)k * N + n] : 0.f; if (scale) v *= scale[k]; vb[i] = v; }
;     }
;     __syncthreads();
; #pragma unroll
;     for (int i = 0; i < 8; ++i) { tile[(ty + 8 * i) * 65 + tx] = va[i]; if (has1) tile[4160 + (ty + 8 * i) * 65 + tx] = vb[i]; }
.LBB0_274:
	s_or_b64 exec, exec, s[24:25]
	s_and_b64 vcc, exec, s[6:7]
	s_cbranch_vccnz .LBB0_276
	v_lshl_add_u64 v[10:11], v[10:11], 2, s[16:17]
	global_load_dword v229, v[10:11], off offset:224
.LBB0_276:
	s_mov_b64 s[6:7], -1
	s_and_b64 vcc, exec, s[26:27]
	s_barrier
	s_waitcnt vmcnt(0)
	s_cmp_lg_u64 s[18:19], 0
	s_cbranch_scc0 .Lcvs_a
	v_mul_f32_e32 v9, v9, v214
	v_mul_f32_e32 v21, v21, v215
	v_mul_f32_e32 v22, v22, v216
	v_mul_f32_e32 v23, v23, v217
	v_mul_f32_e32 v24, v24, v218
	v_mul_f32_e32 v25, v25, v219
	v_mul_f32_e32 v26, v26, v220
	v_mul_f32_e32 v27, v27, v221
	v_mul_f32_e32 v0, v0, v222
	v_mul_f32_e32 v1, v1, v223
	v_mul_f32_e32 v2, v2, v224
	v_mul_f32_e32 v3, v3, v225
	v_mul_f32_e32 v4, v4, v226
	v_mul_f32_e32 v5, v5, v227
	v_mul_f32_e32 v6, v6, v228
	v_mul_f32_e32 v7, v7, v229
.Lcvs_a:
	ds_write_b32 v17, v9
	s_cbranch_vccz .LBB0_278
	ds_write_b32 v17, v21 offset:2080
	ds_write_b32 v17, v22 offset:4160
	s_mov_b64 s[6:7], 0

; __device__ __forceinline__ void conv_matrix(const float* __restrict__ src, int K, int N, int Npad, bf16_t* __restrict__ dst, const float* __restrict__ scale, float* tile) {
;     ...
; #pragma unroll
;     for (int i = 0; i < 8; ++i) { const int k = k0a + ty + 8 * i, n = n0a + tx; float v = (n < N) ? src[(size_t)k * N + n] : 0.f; if (scale) v *= scale[k]; va[i] = v; }
.LBB0_295:
	s_or_b64 exec, exec, s[6:7]
	v_cndmask_b32_e64 v21, 0, 1, s[18:19]
	v_cmp_ne_u32_e64 s[6:7], 1, v21
	s_andn2_b64 vcc, exec, s[18:19]
	s_cbranch_vccnz .LBB0_297
	v_lshl_add_u64 v[22:23], v[10:11], 2, s[16:17]
	global_load_dword v230, v[22:23], off

; __device__ __forceinline__ void conv_matrix(const float* __restrict__ src, int K, int N, int Npad, bf16_t* __restrict__ dst, const float* __restrict__ scale, float* tile) {
;     ...
; #pragma unroll
;     for (int i = 0; i < 8; ++i) { const int k = k0a + ty + 8 * i, n = n0a + tx; float v = (n < N) ? src[(size_t)k * N + n] : 0.f; if (scale) v *= scale[k]; va[i] = v; }
.LBB0_299:
	s_or_b64 exec, exec, s[24:25]
	s_and_b64 vcc, exec, s[6:7]
	s_cbranch_vccnz .LBB0_301
	v_lshl_add_u64 v[22:23], v[10:11], 2, s[16:17]
	global_load_dword v231, v[22:23], off offset:32

; __device__ __forceinline__ void conv_matrix(const float* __restrict__ src, int K, int N, int Npad, bf16_t* __restrict__ dst, const float* __restrict__ scale, float* tile) {
;     ...
; #pragma unroll
;     for (int i = 0; i < 8; ++i) { const int k = k0a + ty + 8 * i, n = n0a + tx; float v = (n < N) ? src[(size_t)k * N + n] : 0.f; if (scale) v *= scale[k]; va[i] = v; }
.LBB0_303:
	s_or_b64 exec, exec, s[24:25]
	s_and_b64 vcc, exec, s[6:7]
	s_cbranch_vccnz .LBB0_305
	v_lshl_add_u64 v[24:25], v[10:11], 2, s[16:17]
	global_load_dword v232, v[24:25], off offset:64

; __device__ __forceinline__ void conv_matrix(const float* __restrict__ src, int K, int N, int Npad, bf16_t* __restrict__ dst, const float* __restrict__ scale, float* tile) {
;     ...
; #pragma unroll
;     for (int i = 0; i < 8; ++i) { const int k = k0a + ty + 8 * i, n = n0a + tx; float v = (n < N) ? src[(size_t)k * N + n] : 0.f; if (scale) v *= scale[k]; va[i] = v; }
.LBB0_307:
	s_or_b64 exec, exec, s[24:25]
	s_and_b64 vcc, exec, s[6:7]
	s_cbranch_vccnz .LBB0_309
	v_lshl_add_u64 v[24:25], v[10:11], 2, s[16:17]
	global_load_dword v233, v[24:25], off offset:96

; __device__ __forceinline__ void conv_matrix(const float* __restrict__ src, int K, int N, int Npad, bf16_t* __restrict__ dst, const float* __restrict__ scale, float* tile) {
;     ...
; #pragma unroll
;     for (int i = 0; i < 8; ++i) { const int k = k0a + ty + 8 * i, n = n0a + tx; float v = (n < N) ? src[(size_t)k * N + n] : 0.f; if (scale) v *= scale[k]; va[i] = v; }
.LBB0_311:
	s_or_b64 exec, exec, s[24:25]
	s_and_b64 vcc, exec, s[6:7]
	s_cbranch_vccnz .LBB0_313
	v_lshl_add_u64 v[26:27], v[10:11], 2, s[16:17]
	global_load_dword v234, v[26:27], off offset:128

; __device__ __forceinline__ void conv_matrix(const float* __restrict__ src, int K, int N, int Npad, bf16_t* __restrict__ dst, const float* __restrict__ scale, float* tile) {
;     ...
; #pragma unroll
;     for (int i = 0; i < 8; ++i) { const int k = k0a + ty + 8 * i, n = n0a + tx; float v = (n < N) ? src[(size_t)k * N + n] : 0.f; if (scale) v *= scale[k]; va[i] = v; }
.LBB0_315:
	s_or_b64 exec, exec, s[24:25]
	s_and_b64 vcc, exec, s[6:7]
	s_cbranch_vccnz .LBB0_317
	v_lshl_add_u64 v[26:27], v[10:11], 2, s[16:17]
	global_load_dword v235, v[26:27], off offset:160

; __device__ __forceinline__ void conv_matrix(const float* __restrict__ src, int K, int N, int Npad, bf16_t* __restrict__ dst, const float* __restrict__ scale, float* tile) {
;     ...
; #pragma unroll
;     for (int i = 0; i < 8; ++i) { const int k = k0a + ty + 8 * i, n = n0a + tx; float v = (n < N) ? src[(size_t)k * N + n] : 0.f; if (scale) v *= scale[k]; va[i] = v; }
.LBB0_319:
	s_or_b64 exec, exec, s[24:25]
	s_and_b64 vcc, exec, s[6:7]
	s_cbranch_vccnz .LBB0_321
	v_lshl_add_u64 v[28:29], v[10:11], 2, s[16:17]
	global_load_dword v236, v[28:29], off offset:192

; __device__ __forceinline__ void conv_matrix(const float* __restrict__ src, int K, int N, int Npad, bf16_t* __restrict__ dst, const float* __restrict__ scale, float* tile) {
;     ...
; #pragma unroll
;     for (int i = 0; i < 8; ++i) { const int k = k0a + ty + 8 * i, n = n0a + tx; float v = (n < N) ? src[(size_t)k * N + n] : 0.f; if (scale) v *= scale[k]; va[i] = v; }
.LBB0_323:
	s_or_b64 exec, exec, s[24:25]
	s_and_b64 vcc, exec, s[6:7]
	s_cbranch_vccnz .LBB0_325
	v_lshl_add_u64 v[10:11], v[10:11], 2, s[16:17]
	global_load_dword v237, v[10:11], off offset:224

; __device__ __forceinline__ void conv_matrix(const float* __restrict__ src, int K, int N, int Npad, bf16_t* __restrict__ dst, const float* __restrict__ scale, float* tile) {
;     ...
; #pragma unroll
;       for (int i = 0; i < 8; ++i) { const int k = k0b + ty + 8 * i, n = n0b + tx; float v = (n < N) ? src[(size_t)k * N + n] : 0.f; if (scale) v *= scale[k]; vb[i] = v; }
.LBB0_328:
	s_or_b64 exec, exec, s[24:25]
	s_and_b64 vcc, exec, s[6:7]
	s_cbranch_vccnz .LBB0_330
	v_lshl_add_u64 v[2:3], v[10:11], 2, s[16:17]
	global_load_dword v238, v[2:3], off

; __device__ __forceinline__ void conv_matrix(const float* __restrict__ src, int K, int N, int Npad, bf16_t* __restrict__ dst, const float* __restrict__ scale, float* tile) {
;     ...
; #pragma unroll
;       for (int i = 0; i < 8; ++i) { const int k = k0b + ty + 8 * i, n = n0b + tx; float v = (n < N) ? src[(size_t)k * N + n] : 0.f; if (scale) v *= scale[k]; vb[i] = v; }
.LBB0_332:
	s_or_b64 exec, exec, s[24:25]
	s_and_b64 vcc, exec, s[6:7]
	s_cbranch_vccnz .LBB0_334
	v_lshl_add_u64 v[2:3], v[10:11], 2, s[16:17]
	global_load_dword v239, v[2:3], off offset:32

; __device__ __forceinline__ void conv_matrix(const float* __restrict__ src, int K, int N, int Npad, bf16_t* __restrict__ dst, const float* __restrict__ scale, float* tile) {
;     ...
; #pragma unroll
;       for (int i = 0; i < 8; ++i) { const int k = k0b + ty + 8 * i, n = n0b + tx; float v = (n < N) ? src[(size_t)k * N + n] : 0.f; if (scale) v *= scale[k]; vb[i] = v; }
.LBB0_336:
	s_or_b64 exec, exec, s[24:25]
	s_and_b64 vcc, exec, s[6:7]
	s_cbranch_vccnz .LBB0_338
	v_lshl_add_u64 v[4:5], v[10:11], 2, s[16:17]
	global_load_dword v240, v[4:5], off offset:64

; __device__ __forceinline__ void conv_matrix(const float* __restrict__ src, int K, int N, int Npad, bf16_t* __restrict__ dst, const float* __restrict__ scale, float* tile) {
;     ...
; #pragma unroll
;       for (int i = 0; i < 8; ++i) { const int k = k0b + ty + 8 * i, n = n0b + tx; float v = (n < N) ? src[(size_t)k * N + n] : 0.f; if (scale) v *= scale[k]; vb[i] = v; }
.LBB0_340:
	s_or_b64 exec, exec, s[24:25]
	s_and_b64 vcc, exec, s[6:7]
	s_cbranch_vccnz .LBB0_342
	v_lshl_add_u64 v[4:5], v[10:11], 2, s[16:17]
	global_load_dword v241, v[4:5], off offset:96

; __device__ __forceinline__ void conv_matrix(const float* __restrict__ src, int K, int N, int Npad, bf16_t* __restrict__ dst, const float* __restrict__ scale, float* tile) {
;     ...
; #pragma unroll
;       for (int i = 0; i < 8; ++i) { const int k = k0b + ty + 8 * i, n = n0b + tx; float v = (n < N) ? src[(size_t)k * N + n] : 0.f; if (scale) v *= scale[k]; vb[i] = v; }
.LBB0_344:
	s_or_b64 exec, exec, s[24:25]
	s_and_b64 vcc, exec, s[6:7]
	s_cbranch_vccnz .LBB0_346
	v_lshl_add_u64 v[6:7], v[10:11], 2, s[16:17]
	global_load_dword v242, v[6:7], off offset:128

; __device__ __forceinline__ void conv_matrix(const float* __restrict__ src, int K, int N, int Npad, bf16_t* __restrict__ dst, const float* __restrict__ scale, float* tile) {
;     ...
; #pragma unroll
;       for (int i = 0; i < 8; ++i) { const int k = k0b + ty + 8 * i, n = n0b + tx; float v = (n < N) ? src[(size_t)k * N + n] : 0.f; if (scale) v *= scale[k]; vb[i] = v; }
.LBB0_348:
	s_or_b64 exec, exec, s[24:25]
	s_and_b64 vcc, exec, s[6:7]
	s_cbranch_vccnz .LBB0_350
	v_lshl_add_u64 v[6:7], v[10:11], 2, s[16:17]
	global_load_dword v243, v[6:7], off offset:160

; __device__ __forceinline__ void conv_matrix(const float* __restrict__ src, int K, int N, int Npad, bf16_t* __restrict__ dst, const float* __restrict__ scale, float* tile) {
;     ...
; #pragma unroll
;       for (int i = 0; i < 8; ++i) { const int k = k0b + ty + 8 * i, n = n0b + tx; float v = (n < N) ? src[(size_t)k * N + n] : 0.f; if (scale) v *= scale[k]; vb[i] = v; }
.LBB0_352:
	s_or_b64 exec, exec, s[24:25]
	s_and_b64 vcc, exec, s[6:7]
	s_cbranch_vccnz .LBB0_354
	v_lshl_add_u64 v[28:29], v[10:11], 2, s[16:17]
	global_load_dword v244, v[28:29], off offset:192

; __device__ __forceinline__ void conv_matrix(const float* __restrict__ src, int K, int N, int Npad, bf16_t* __restrict__ dst, const float* __restrict__ scale, float* tile) {
;     ...
; #pragma unroll
;       for (int i = 0; i < 8; ++i) { const int k = k0b + ty + 8 * i, n = n0b + tx; float v = (n < N) ? src[(size_t)k * N + n] : 0.f; if (scale) v *= scale[k]; vb[i] = v; }
;     }
;     __syncthreads();
; #pragma unroll
;     for (int i = 0; i < 8; ++i) { tile[(ty + 8 * i) * 65 + tx] = va[i]; if (has1) tile[4160 + (ty + 8 * i) * 65 + tx] = vb[i]; }
.LBB0_356:
	s_or_b64 exec, exec, s[24:25]
	s_and_b64 vcc, exec, s[6:7]
	s_cbranch_vccnz .LBB0_358
	v_lshl_add_u64 v[10:11], v[10:11], 2, s[16:17]
	global_load_dword v245, v[10:11], off offset:224
.LBB0_358:
	s_sub_i32 s8, 0, s38
	s_mov_b64 s[6:7], -1
	s_and_b64 vcc, exec, s[22:23]
	s_barrier
	s_waitcnt vmcnt(0)
	s_cmp_lg_u64 s[18:19], 0
	s_cbranch_scc0 .Lcvs_b
	v_mul_f32_e32 v20, v20, v230
	v_mul_f32_e32 v21, v21, v231
	v_mul_f32_e32 v22, v22, v232
	v_mul_f32_e32 v23, v23, v233
	v_mul_f32_e32 v24, v24, v234
	v_mul_f32_e32 v25, v25, v235
	v_mul_f32_e32 v26, v26, v236
	v_mul_f32_e32 v27, v27, v237
	v_mul_f32_e32 v0, v0, v238
	v_mul_f32_e32 v1, v1, v239
	v_mul_f32_e32 v2, v2, v240
	v_mul_f32_e32 v3, v3, v241
	v_mul_f32_e32 v4, v4, v242
	v_mul_f32_e32 v5, v5, v243
	v_mul_f32_e32 v6, v6, v244
	v_mul_f32_e32 v7, v7, v245
.Lcvs_b:
	ds_write_b32 v16, v20
	s_cbranch_vccz .LBB0_360
	ds_write_b32 v16, v21 offset:2080
	ds_write_b32 v16, v22 offset:4160
	s_mov_b64 s[6:7], 0

; #define PG8_STAGE(bufoff, gbase, voff) do { _Pragma("unroll") for (int _i = 0; _i < 2; ++_i) \
;     __builtin_amdgcn_global_load_lds((const unsigned*)((const char*)(gbase) + (voff)[_i]), (LAS unsigned*)(lds + (bufoff) + ldsw + _i * 8192), 16, 0, 0); } while (0)
; #define PG8_LDA(dst, b, h) do { _Pragma("unroll") for (int m = 0; m < 4; ++m) _Pragma("unroll") for (int k = 0; k < 2; ++k) dst[m][k] = *(const LAS bf16x8*)(lds + PG8_SA(b, h) + aoff + m * 2048 + k * 1024); } while (0)
; #define PG8_LDB(dst, b, h) do { _Pragma("unroll") for (int n = 0; n < 2; ++n) _Pragma("unroll") for (int k = 0; k < 2; ++k) dst[n][k] = *(const LAS bf16x8*)(lds + PG8_SB(b, h) + boff + n * 2048 + k * 1024); } while (0)
; #define PG8_MMA(ai, bj, At, Bt) do { __builtin_amdgcn_s_setprio(1); _Pragma("unroll") for (int m = 0; m < 4; ++m) _Pragma("unroll") for (int n = 0; n < 2; ++n) _Pragma("unroll") for (int k = 0; k < 2; ++k) \
;     acc[ai][bj][m][n] = __builtin_amdgcn_mfma_f32_16x16x32_bf16(Bt[n][k], At[m][k], acc[ai][bj][m][n], 0, 0, 0); __builtin_amdgcn_s_setprio(0); } while (0)
; #define PG8_WAIT_L(n) asm volatile("s_waitcnt lgkmcnt(" #n ")" ::: "memory")
; #define PG8_BAR __builtin_amdgcn_s_barrier()
; #define PG8_SCHED __builtin_amdgcn_sched_barrier(0)
; template <class Epi, class Sched>
; __device__ __forceinline__ void gemm_phase(LAS unsigned char* lds, const Gemm g, const Sched& S, const Epi& E) {
;     ...
;       PG8_LDB(B0, 0, 0); PG8_SCHED; PG8_LDA(At, 0, 0); PG8_STAGE(PG8_SA(1, 1), a1 + hstepA, voffA);
;       PG8_WAIT_L(8); PG8_BAR; PG8_WAIT_L(0); PG8_MMA(0, 0, At, B0); PG8_BAR; PG8_SCHED;
;       PG8_LDB(B1, 0, 1); PG8_STAGE(PG8_SB(0, 0), b2, voffB);
;       PG8_BAR; PG8_WAIT_L(0); PG8_MMA(0, 1, At, B1); PG8_BAR;
;       PG8_LDA(At, 0, 1); PG8_STAGE(PG8_SA(0, 0), a2, voffA);
;       PG8_BAR; PG8_WAIT_L(0); PG8_MMA(1, 0, At, B0); PG8_BAR; PG8_SCHED;
.LBB0_1541:
	s_add_u32 s36, s78, 0xfffc0080
	s_addc_u32 s37, s79, -1
	s_add_i32 s76, 16, 0x10000
	v_add_u32_e32 v153, s76, v150
	ds_read_b128 v[136:139], v153
	ds_read_b128 v[140:143], v153 offset:1024
	ds_read_b128 v[146:149], v153 offset:2048
	ds_read_b128 v[154:157], v153 offset:3072
	s_cmp_eq_u32 s84, 12
	s_cselect_b32 s83, s9, s37
	s_cselect_b32 s82, s11, s36
	s_cselect_b32 s39, s23, s27
	s_cselect_b32 s38, s24, s25
	v_lshl_add_u64 v[214:215], s[78:79], 0, v[132:133]
	s_add_i32 m0, s69, 0xc000
	ds_read_b128 v[158:161], v152
	ds_read_b128 v[162:165], v152 offset:1024
	ds_read_b128 v[166:169], v152 offset:2048
	ds_read_b128 v[170:173], v152 offset:3072
	ds_read_b128 v[174:177], v152 offset:4096
	ds_read_b128 v[178:181], v152 offset:5120
	ds_read_b128 v[182:185], v152 offset:6144
	ds_read_b128 v[198:201], v152 offset:7168
	global_load_lds_dwordx4 v[214:215], off
	v_lshl_add_u64 v[214:215], s[78:79], 0, v[134:135]
	s_add_i32 m0, s69, 0xe000
	s_nop 0
	global_load_lds_dwordx4 v[214:215], off
	s_waitcnt lgkmcnt(8)
	s_barrier
	s_waitcnt lgkmcnt(0)
	s_setprio 1
	s_waitcnt lgkmcnt(0)
	v_mfma_f32_16x16x32_bf16 v[124:127], v[136:139], v[158:161], v[124:127]
	v_mfma_f32_16x16x32_bf16 v[120:123], v[146:149], v[158:161], v[120:123]
	v_mfma_f32_16x16x32_bf16 v[108:111], v[136:139], v[166:169], v[108:111]
	v_mfma_f32_16x16x32_bf16 v[104:107], v[146:149], v[166:169], v[104:107]
	v_mfma_f32_16x16x32_bf16 v[92:95], v[136:139], v[174:177], v[92:95]
	v_mfma_f32_16x16x32_bf16 v[88:91], v[146:149], v[174:177], v[88:91]
	v_mfma_f32_16x16x32_bf16 v[76:79], v[136:139], v[182:185], v[76:79]
	v_mfma_f32_16x16x32_bf16 v[72:75], v[146:149], v[182:185], v[72:75]
	v_mfma_f32_16x16x32_bf16 v[124:127], v[140:143], v[162:165], v[124:127]
	v_mfma_f32_16x16x32_bf16 v[120:123], v[154:157], v[162:165], v[120:123]
	v_mfma_f32_16x16x32_bf16 v[108:111], v[140:143], v[170:173], v[108:111]
	v_mfma_f32_16x16x32_bf16 v[104:107], v[154:157], v[170:173], v[104:107]
	v_mfma_f32_16x16x32_bf16 v[92:95], v[140:143], v[178:181], v[92:95]
	v_mfma_f32_16x16x32_bf16 v[88:91], v[154:157], v[178:181], v[88:91]
	v_mfma_f32_16x16x32_bf16 v[76:79], v[140:143], v[198:201], v[76:79]
	v_mfma_f32_16x16x32_bf16 v[72:75], v[154:157], v[198:201], v[72:75]
	s_setprio 0
	s_barrier
	s_add_i32 s77, 16, 0x14000
	s_add_i32 s36, s76, s68
	v_add_u32_e32 v153, s77, v150
	v_lshl_add_u64 v[230:231], s[38:39], 0, v[128:129]
	s_mov_b32 m0, s36
	ds_read_b128 v[214:217], v153
	ds_read_b128 v[218:221], v153 offset:1024
	ds_read_b128 v[222:225], v153 offset:2048
	ds_read_b128 v[226:229], v153 offset:3072
	global_load_lds_dwordx4 v[230:231], off
	v_lshl_add_u64 v[232:233], s[38:39], 0, v[130:131]
	s_add_i32 m0, s36, 0x2000
	s_nop 0
	global_load_lds_dwordx4 v[232:233], off
	s_barrier
	s_waitcnt lgkmcnt(0)
	s_setprio 1
	s_waitcnt lgkmcnt(0)
	v_mfma_f32_16x16x32_bf16 v[116:119], v[214:217], v[158:161], v[116:119]
	v_mfma_f32_16x16x32_bf16 v[112:115], v[222:225], v[158:161], v[112:115]
	v_mfma_f32_16x16x32_bf16 v[100:103], v[214:217], v[166:169], v[100:103]
	v_mfma_f32_16x16x32_bf16 v[96:99], v[222:225], v[166:169], v[96:99]
	v_mfma_f32_16x16x32_bf16 v[84:87], v[214:217], v[174:177], v[84:87]
	v_mfma_f32_16x16x32_bf16 v[80:83], v[222:225], v[174:177], v[80:83]
	v_mfma_f32_16x16x32_bf16 v[68:71], v[214:217], v[182:185], v[68:71]
	v_mfma_f32_16x16x32_bf16 v[64:67], v[222:225], v[182:185], v[64:67]
	v_mfma_f32_16x16x32_bf16 v[116:119], v[218:221], v[162:165], v[116:119]
	v_mfma_f32_16x16x32_bf16 v[112:115], v[226:229], v[162:165], v[112:115]
	v_mfma_f32_16x16x32_bf16 v[100:103], v[218:221], v[170:173], v[100:103]
	v_mfma_f32_16x16x32_bf16 v[96:99], v[226:229], v[170:173], v[96:99]
	v_mfma_f32_16x16x32_bf16 v[84:87], v[218:221], v[178:181], v[84:87]
	v_mfma_f32_16x16x32_bf16 v[80:83], v[226:229], v[178:181], v[80:83]
	v_mfma_f32_16x16x32_bf16 v[68:71], v[218:221], v[198:201], v[68:71]
	v_mfma_f32_16x16x32_bf16 v[64:67], v[226:229], v[198:201], v[64:67]
	s_setprio 0
	s_mov_b32 m0, s69
	v_lshl_add_u64 v[234:235], s[82:83], 0, v[128:129]
	s_barrier
	ds_read_b128 v[158:161], v152 offset:16384
	ds_read_b128 v[162:165], v152 offset:17408
	ds_read_b128 v[166:169], v152 offset:18432
	ds_read_b128 v[170:173], v152 offset:19456
	ds_read_b128 v[174:177], v152 offset:20480
	ds_read_b128 v[178:181], v152 offset:21504
	ds_read_b128 v[182:185], v152 offset:22528
	ds_read_b128 v[198:201], v152 offset:23552
	global_load_lds_dwordx4 v[234:235], off
	v_lshl_add_u64 v[236:237], s[82:83], 0, v[130:131]
	s_mov_b32 m0, s74
	s_nop 0
	global_load_lds_dwordx4 v[236:237], off
	s_barrier
	s_waitcnt lgkmcnt(0)
	s_setprio 1
	s_waitcnt lgkmcnt(0)
	v_mfma_f32_16x16x32_bf16 v[60:63], v[136:139], v[158:161], v[60:63]
	v_mfma_f32_16x16x32_bf16 v[56:59], v[146:149], v[158:161], v[56:59]
	v_mfma_f32_16x16x32_bf16 v[44:47], v[136:139], v[166:169], v[44:47]
	v_mfma_f32_16x16x32_bf16 v[40:43], v[146:149], v[166:169], v[40:43]
	v_mfma_f32_16x16x32_bf16 v[28:31], v[136:139], v[174:177], v[28:31]
	v_mfma_f32_16x16x32_bf16 v[24:27], v[146:149], v[174:177], v[24:27]
	v_mfma_f32_16x16x32_bf16 v[12:15], v[136:139], v[182:185], v[12:15]
	v_mfma_f32_16x16x32_bf16 v[8:11], v[146:149], v[182:185], v[8:11]
	v_mfma_f32_16x16x32_bf16 v[60:63], v[140:143], v[162:165], v[60:63]
	v_mfma_f32_16x16x32_bf16 v[56:59], v[154:157], v[162:165], v[56:59]
	v_mfma_f32_16x16x32_bf16 v[44:47], v[140:143], v[170:173], v[44:47]
	v_mfma_f32_16x16x32_bf16 v[40:43], v[154:157], v[170:173], v[40:43]
	v_mfma_f32_16x16x32_bf16 v[28:31], v[140:143], v[178:181], v[28:31]
	v_mfma_f32_16x16x32_bf16 v[24:27], v[154:157], v[178:181], v[24:27]
	v_mfma_f32_16x16x32_bf16 v[12:15], v[140:143], v[198:201], v[12:15]
	v_mfma_f32_16x16x32_bf16 v[8:11], v[154:157], v[198:201], v[8:11]
	s_setprio 0
	s_barrier
; #define PG8_STAGE(bufoff, gbase, voff) do { _Pragma("unroll") for (int _i = 0; _i < 2; ++_i) \
;     __builtin_amdgcn_global_load_lds((const unsigned*)((const char*)(gbase) + (voff)[_i]), (LAS unsigned*)(lds + (bufoff) + ldsw + _i * 8192), 16, 0, 0); } while (0)
; #define PG8_LDA(dst, b, h) do { _Pragma("unroll") for (int m = 0; m < 4; ++m) _Pragma("unroll") for (int k = 0; k < 2; ++k) dst[m][k] = *(const LAS bf16x8*)(lds + PG8_SA(b, h) + aoff + m * 2048 + k * 1024); } while (0)
; #define PG8_LDB(dst, b, h) do { _Pragma("unroll") for (int n = 0; n < 2; ++n) _Pragma("unroll") for (int k = 0; k < 2; ++k) dst[n][k] = *(const LAS bf16x8*)(lds + PG8_SB(b, h) + boff + n * 2048 + k * 1024); } while (0)
; #define PG8_MMA(ai, bj, At, Bt) do { __builtin_amdgcn_s_setprio(1); _Pragma("unroll") for (int m = 0; m < 4; ++m) _Pragma("unroll") for (int n = 0; n < 2; ++n) _Pragma("unroll") for (int k = 0; k < 2; ++k) \
;     acc[ai][bj][m][n] = __builtin_amdgcn_mfma_f32_16x16x32_bf16(Bt[n][k], At[m][k], acc[ai][bj][m][n], 0, 0, 0); __builtin_amdgcn_s_setprio(0); } while (0)
; #define PG8_WAIT_V(n) asm volatile("s_waitcnt vmcnt(" #n ")" ::: "memory")
; #define PG8_WAIT_L(n) asm volatile("s_waitcnt lgkmcnt(" #n ")" ::: "memory")
; #define PG8_BAR __builtin_amdgcn_s_barrier()
; #define PG8_SCHED __builtin_amdgcn_sched_barrier(0)
; template <class Epi, class Sched>
; __device__ __forceinline__ void gemm_phase(LAS unsigned char* lds, const Gemm g, const Sched& S, const Epi& E) {
;     ...
;       PG8_STAGE(PG8_SB(0, 1), b2 + hstepB, voffB);
;       PG8_WAIT_V(6); PG8_BAR; PG8_MMA(1, 1, At, B1); PG8_BAR;
;       PG8_LDB(B0, 1, 0); PG8_SCHED; PG8_LDA(At, 1, 0); PG8_STAGE(PG8_SA(0, 1), a2 + hstepA, voffA);
;       PG8_WAIT_L(8); PG8_BAR; PG8_WAIT_L(0); PG8_MMA(0, 0, At, B0); PG8_BAR; PG8_SCHED;
;       PG8_LDB(B1, 1, 1); PG8_STAGE(PG8_SB(1, 0), b3, voffB);
;       PG8_BAR; PG8_WAIT_L(0); PG8_MMA(0, 1, At, B1); PG8_BAR;
	s_add_u32 s36, s38, 0x40000
	s_addc_u32 s37, s39, 0
	s_add_i32 s76, s77, s68
	v_lshl_add_u64 v[136:137], s[36:37], 0, v[128:129]
	s_mov_b32 m0, s76
	s_nop 0
	global_load_lds_dwordx4 v[136:137], off
	v_lshl_add_u64 v[136:137], s[36:37], 0, v[130:131]
	s_add_i32 m0, s76, 0x2000
	s_nop 0
	global_load_lds_dwordx4 v[136:137], off
	s_waitcnt vmcnt(6)
	s_barrier
	s_setprio 1
	v_mfma_f32_16x16x32_bf16 v[52:55], v[214:217], v[158:161], v[52:55]
	v_mfma_f32_16x16x32_bf16 v[48:51], v[222:225], v[158:161], v[48:51]
	v_mfma_f32_16x16x32_bf16 v[36:39], v[214:217], v[166:169], v[36:39]
	v_mfma_f32_16x16x32_bf16 v[32:35], v[222:225], v[166:169], v[32:35]
	v_mfma_f32_16x16x32_bf16 v[20:23], v[214:217], v[174:177], v[20:23]
	v_mfma_f32_16x16x32_bf16 v[16:19], v[222:225], v[174:177], v[16:19]
	v_mfma_f32_16x16x32_bf16 v[4:7], v[214:217], v[182:185], v[4:7]
	v_mfma_f32_16x16x32_bf16 v[0:3], v[222:225], v[182:185], v[0:3]
	v_mfma_f32_16x16x32_bf16 v[52:55], v[218:221], v[162:165], v[52:55]
	v_mfma_f32_16x16x32_bf16 v[48:51], v[226:229], v[162:165], v[48:51]
	v_mfma_f32_16x16x32_bf16 v[36:39], v[218:221], v[170:173], v[36:39]
	v_mfma_f32_16x16x32_bf16 v[32:35], v[226:229], v[170:173], v[32:35]
	v_mfma_f32_16x16x32_bf16 v[20:23], v[218:221], v[178:181], v[20:23]
	v_mfma_f32_16x16x32_bf16 v[16:19], v[226:229], v[178:181], v[16:19]
	v_mfma_f32_16x16x32_bf16 v[4:7], v[218:221], v[198:201], v[4:7]
	v_mfma_f32_16x16x32_bf16 v[0:3], v[226:229], v[198:201], v[0:3]
	s_setprio 0
	s_add_i32 s76, 16, 0x18000
	v_add_u32_e32 v153, s76, v150
	s_barrier
	ds_read_b128 v[136:139], v153
	ds_read_b128 v[140:143], v153 offset:1024
	ds_read_b128 v[146:149], v153 offset:2048
	ds_read_b128 v[154:157], v153 offset:3072
	s_add_u32 s36, s82, 0x40000
	s_addc_u32 s37, s83, 0
	s_mov_b32 m0, s75
	v_lshl_add_u64 v[214:215], s[36:37], 0, v[128:129]
	ds_read_b128 v[158:161], v152 offset:32768
	ds_read_b128 v[162:165], v152 offset:33792
	ds_read_b128 v[166:169], v152 offset:34816
	ds_read_b128 v[170:173], v152 offset:35840
	ds_read_b128 v[174:177], v152 offset:36864
	ds_read_b128 v[178:181], v152 offset:37888
	ds_read_b128 v[182:185], v152 offset:38912
	ds_read_b128 v[198:201], v152 offset:39936
	global_load_lds_dwordx4 v[214:215], off
	v_lshl_add_u64 v[214:215], s[36:37], 0, v[130:131]
	s_mov_b32 m0, s86
	s_nop 0
	global_load_lds_dwordx4 v[214:215], off
	s_waitcnt lgkmcnt(8)
	s_barrier
	s_waitcnt lgkmcnt(0)
	s_setprio 1
	s_waitcnt lgkmcnt(0)
	v_mfma_f32_16x16x32_bf16 v[124:127], v[136:139], v[158:161], v[124:127]
	v_mfma_f32_16x16x32_bf16 v[120:123], v[146:149], v[158:161], v[120:123]
	v_mfma_f32_16x16x32_bf16 v[108:111], v[136:139], v[166:169], v[108:111]
	v_mfma_f32_16x16x32_bf16 v[104:107], v[146:149], v[166:169], v[104:107]
	v_mfma_f32_16x16x32_bf16 v[92:95], v[136:139], v[174:177], v[92:95]
	v_mfma_f32_16x16x32_bf16 v[88:91], v[146:149], v[174:177], v[88:91]
	v_mfma_f32_16x16x32_bf16 v[76:79], v[136:139], v[182:185], v[76:79]
	v_mfma_f32_16x16x32_bf16 v[72:75], v[146:149], v[182:185], v[72:75]
	v_mfma_f32_16x16x32_bf16 v[124:127], v[140:143], v[162:165], v[124:127]
	v_mfma_f32_16x16x32_bf16 v[120:123], v[154:157], v[162:165], v[120:123]
	v_mfma_f32_16x16x32_bf16 v[108:111], v[140:143], v[170:173], v[108:111]
	v_mfma_f32_16x16x32_bf16 v[104:107], v[154:157], v[170:173], v[104:107]
	v_mfma_f32_16x16x32_bf16 v[92:95], v[140:143], v[178:181], v[92:95]
	v_mfma_f32_16x16x32_bf16 v[88:91], v[154:157], v[178:181], v[88:91]
	v_mfma_f32_16x16x32_bf16 v[76:79], v[140:143], v[198:201], v[76:79]
	v_mfma_f32_16x16x32_bf16 v[72:75], v[154:157], v[198:201], v[72:75]
	s_setprio 0
	s_barrier
	s_add_i32 s77, 16, 0x1c000
	s_add_i32 s36, s76, s68
	v_add_u32_e32 v153, s77, v150
	v_lshl_add_u64 v[230:231], v[230:231], 0, s[62:63]
	s_mov_b32 m0, s36
	ds_read_b128 v[214:217], v153
	ds_read_b128 v[218:221], v153 offset:1024
	ds_read_b128 v[222:225], v153 offset:2048
	ds_read_b128 v[226:229], v153 offset:3072
	global_load_lds_dwordx4 v[230:231], off
	v_lshl_add_u64 v[230:231], v[232:233], 0, s[62:63]
	s_add_i32 m0, s36, 0x2000
	s_nop 0
	global_load_lds_dwordx4 v[230:231], off
	s_barrier
	s_waitcnt lgkmcnt(0)
	s_setprio 1
	s_waitcnt lgkmcnt(0)
	v_mfma_f32_16x16x32_bf16 v[116:119], v[214:217], v[158:161], v[116:119]
	v_mfma_f32_16x16x32_bf16 v[112:115], v[222:225], v[158:161], v[112:115]
	v_mfma_f32_16x16x32_bf16 v[100:103], v[214:217], v[166:169], v[100:103]
	v_mfma_f32_16x16x32_bf16 v[96:99], v[222:225], v[166:169], v[96:99]
	v_mfma_f32_16x16x32_bf16 v[84:87], v[214:217], v[174:177], v[84:87]
	v_mfma_f32_16x16x32_bf16 v[80:83], v[222:225], v[174:177], v[80:83]
	v_mfma_f32_16x16x32_bf16 v[68:71], v[214:217], v[182:185], v[68:71]
	v_mfma_f32_16x16x32_bf16 v[64:67], v[222:225], v[182:185], v[64:67]
	v_mfma_f32_16x16x32_bf16 v[116:119], v[218:221], v[162:165], v[116:119]
	v_mfma_f32_16x16x32_bf16 v[112:115], v[226:229], v[162:165], v[112:115]
	v_mfma_f32_16x16x32_bf16 v[100:103], v[218:221], v[170:173], v[100:103]
	v_mfma_f32_16x16x32_bf16 v[96:99], v[226:229], v[170:173], v[96:99]
	v_mfma_f32_16x16x32_bf16 v[84:87], v[218:221], v[178:181], v[84:87]
	v_mfma_f32_16x16x32_bf16 v[80:83], v[226:229], v[178:181], v[80:83]
	v_mfma_f32_16x16x32_bf16 v[68:71], v[218:221], v[198:201], v[68:71]
	v_mfma_f32_16x16x32_bf16 v[64:67], v[226:229], v[198:201], v[64:67]
	s_setprio 0
	s_mov_b32 m0, s87
	v_lshl_add_u64 v[230:231], v[234:235], 0, s[62:63]
	s_barrier
; __device__ __forceinline__ float sigmoidf_(float v) { return __builtin_amdgcn_rcpf(1.0f + __expf(-v)); }
; __device__ __forceinline__ float siluf_(float v) { return v * sigmoidf_(v); }
; __device__ __forceinline__ void store_bf16x4(bf16_t* p, f32x4 v) { u32x2 w; w.x = cvt_pk_bf16(v[0], v[1]); w.y = cvt_pk_bf16(v[2], v[3]); *(u32x2*)p = w; }
; #define PG8_STAGE(bufoff, gbase, voff) do { _Pragma("unroll") for (int _i = 0; _i < 2; ++_i) \
;     __builtin_amdgcn_global_load_lds((const unsigned*)((const char*)(gbase) + (voff)[_i]), (LAS unsigned*)(lds + (bufoff) + ldsw + _i * 8192), 16, 0, 0); } while (0)
; #define PG8_LDA(dst, b, h) do { _Pragma("unroll") for (int m = 0; m < 4; ++m) _Pragma("unroll") for (int k = 0; k < 2; ++k) dst[m][k] = *(const LAS bf16x8*)(lds + PG8_SA(b, h) + aoff + m * 2048 + k * 1024); } while (0)
; #define PG8_WAIT_V(n) asm volatile("s_waitcnt vmcnt(" #n ")" ::: "memory")
; #define PG8_WAIT_L(n) asm volatile("s_waitcnt lgkmcnt(" #n ")" ::: "memory")
; #define PG8_BAR __builtin_amdgcn_s_barrier()
; #define PG8_SCHED __builtin_amdgcn_sched_barrier(0)
; template <class Epi, class Sched>
; __device__ __forceinline__ void gemm_phase(LAS unsigned char* lds, const Gemm g, const Sched& S, const Epi& E) {
;     ...
;       PG8_LDA(At, 1, 1); PG8_STAGE(PG8_SA(1, 0), a3, voffA);
;       PG8_BAR; PG8_WAIT_L(0); PG8_MMA(1, 0, At, B0); PG8_BAR; PG8_SCHED;
;       PG8_STAGE(PG8_SB(1, 1), b3 + hstepB, voffB);
;       PG8_WAIT_V(6); PG8_BAR; PG8_MMA(1, 1, At, B1); PG8_BAR;
;   __device__ __forceinline__ void operator()(const f32x4 (&acc)[2][2][4][2], const pg8::Unit& u, int wr, int wc, int fr, int fq) const {
;     const int pn = u.pn;
;     EPI_LOOP(
;       if (pn < 2) { f32x4 o; for (int j = 0; j < 4; ++j) o[j] = siluf_(v[j]); store_bf16x4(QH + (size_t)row * 512 + col, o); }
;       else if (pn < 6) { const int c = col - 512; const f32x4 lb = *(const f32x4*)(LBj + c); f32x4 o; for (int j = 0; j < 4; ++j) o[j] = lb[j] + (1.f - lb[j]) * sigmoidf_(v[j]); *(f32x4*)(F + (size_t)row * 1024 + c) = o; }
;       else if (pn < 8) { store_bf16x4(VH + (size_t)row * 512 + (col - 1536), v); }
;       else if (pn < 10) { f32x4 o; for (int j = 0; j < 4; ++j) o[j] = siluf_(v[j]); store_bf16x4(G + (size_t)row * 512 + (col - 2048), o); }
;       else { store_bf16x4(CQ + (size_t)row * 768 + (col - 2560), v); }
	ds_read_b128 v[158:161], v152 offset:49152
	ds_read_b128 v[162:165], v152 offset:50176
	ds_read_b128 v[166:169], v152 offset:51200
	ds_read_b128 v[170:173], v152 offset:52224
	ds_read_b128 v[174:177], v152 offset:53248
	ds_read_b128 v[178:181], v152 offset:54272
	ds_read_b128 v[182:185], v152 offset:55296
	ds_read_b128 v[198:201], v152 offset:56320
	global_load_lds_dwordx4 v[230:231], off
	v_lshl_add_u64 v[230:231], v[236:237], 0, s[62:63]
	s_mov_b32 m0, s88
	s_nop 0
	global_load_lds_dwordx4 v[230:231], off
	s_barrier
	s_waitcnt lgkmcnt(0)
	s_setprio 1
	s_waitcnt lgkmcnt(0)
	v_mfma_f32_16x16x32_bf16 v[60:63], v[136:139], v[158:161], v[60:63]
	v_mfma_f32_16x16x32_bf16 v[56:59], v[146:149], v[158:161], v[56:59]
	v_mfma_f32_16x16x32_bf16 v[44:47], v[136:139], v[166:169], v[44:47]
	v_mfma_f32_16x16x32_bf16 v[40:43], v[146:149], v[166:169], v[40:43]
	v_mfma_f32_16x16x32_bf16 v[28:31], v[136:139], v[174:177], v[28:31]
	v_mfma_f32_16x16x32_bf16 v[24:27], v[146:149], v[174:177], v[24:27]
	v_mfma_f32_16x16x32_bf16 v[12:15], v[136:139], v[182:185], v[12:15]
	v_mfma_f32_16x16x32_bf16 v[8:11], v[146:149], v[182:185], v[8:11]
	v_mfma_f32_16x16x32_bf16 v[60:63], v[140:143], v[162:165], v[60:63]
	v_mfma_f32_16x16x32_bf16 v[56:59], v[154:157], v[162:165], v[56:59]
	v_mfma_f32_16x16x32_bf16 v[44:47], v[140:143], v[170:173], v[44:47]
	v_mfma_f32_16x16x32_bf16 v[40:43], v[154:157], v[170:173], v[40:43]
	v_mfma_f32_16x16x32_bf16 v[28:31], v[140:143], v[178:181], v[28:31]
	v_mfma_f32_16x16x32_bf16 v[24:27], v[154:157], v[178:181], v[24:27]
	v_mfma_f32_16x16x32_bf16 v[12:15], v[140:143], v[198:201], v[12:15]
	v_mfma_f32_16x16x32_bf16 v[8:11], v[154:157], v[198:201], v[8:11]
	s_setprio 0
	s_barrier
	s_add_u32 s36, s38, 0x40080
	s_addc_u32 s37, s39, 0
	s_add_i32 s38, s77, s68
	v_lshl_add_u64 v[136:137], s[36:37], 0, v[128:129]
	s_mov_b32 m0, s38
	s_nop 0
	global_load_lds_dwordx4 v[136:137], off
	v_lshl_add_u64 v[136:137], s[36:37], 0, v[130:131]
	s_add_i32 m0, s38, 0x2000
	s_nop 0
	global_load_lds_dwordx4 v[136:137], off
	s_waitcnt vmcnt(6)
	s_barrier
	s_setprio 1
	v_mfma_f32_16x16x32_bf16 v[52:55], v[214:217], v[158:161], v[52:55]
	v_mfma_f32_16x16x32_bf16 v[48:51], v[222:225], v[158:161], v[48:51]
	v_mfma_f32_16x16x32_bf16 v[36:39], v[214:217], v[166:169], v[36:39]
	v_mfma_f32_16x16x32_bf16 v[32:35], v[222:225], v[166:169], v[32:35]
	v_mfma_f32_16x16x32_bf16 v[20:23], v[214:217], v[174:177], v[20:23]
	v_mfma_f32_16x16x32_bf16 v[16:19], v[222:225], v[174:177], v[16:19]
	v_mfma_f32_16x16x32_bf16 v[4:7], v[214:217], v[182:185], v[4:7]
	v_mfma_f32_16x16x32_bf16 v[0:3], v[222:225], v[182:185], v[0:3]
	v_mfma_f32_16x16x32_bf16 v[52:55], v[218:221], v[162:165], v[52:55]
	v_mfma_f32_16x16x32_bf16 v[48:51], v[226:229], v[162:165], v[48:51]
	v_mfma_f32_16x16x32_bf16 v[36:39], v[218:221], v[170:173], v[36:39]
	v_mfma_f32_16x16x32_bf16 v[32:35], v[226:229], v[170:173], v[32:35]
	v_mfma_f32_16x16x32_bf16 v[20:23], v[218:221], v[178:181], v[20:23]
	v_mfma_f32_16x16x32_bf16 v[16:19], v[226:229], v[178:181], v[16:19]
	v_mfma_f32_16x16x32_bf16 v[4:7], v[218:221], v[198:201], v[4:7]
	v_mfma_f32_16x16x32_bf16 v[0:3], v[226:229], v[198:201], v[0:3]
	s_setprio 0
	s_add_i32 s84, s84, 2
	s_add_u32 s78, s78, 0x100
	s_addc_u32 s79, s79, 0
	s_add_u32 s25, s25, 0x100
	s_addc_u32 s27, s27, 0
	s_cmp_gt_u32 s84, 13
	s_barrier
	s_cbranch_scc0 .LBB0_1541
	s_cmp_gt_i32 s8, 1
	s_cselect_b64 s[82:83], -1, 0
	s_cmp_gt_u32 s8, 5
	v_lshl_add_u32 v138, s10, 8, v145
	s_cselect_b64 s[38:39], -1, 0
	s_cmp_gt_u32 s8, 7
	v_lshl_or_b32 v136, s8, 8, v151
	s_cselect_b64 s[84:85], -1, 0
	s_cmp_gt_u32 s8, 9
	v_ashrrev_i32_e32 v139, 31, v138
	v_mad_i64_i32 v[146:147], s[8:9], v138, s64, 0
	s_cselect_b64 s[78:79], -1, 0
	v_lshlrev_b64 v[142:143], 10, v[138:139]
	v_lshlrev_b64 v[140:141], 12, v[138:139]
	s_andn2_b64 vcc, s[82:83], s[38:39]
	s_cbranch_vccz .Llbv_skip
	v_mov_b32_e32 v148, v136
	v_ashrrev_i32_e32 v149, 31, v136
	v_lshlrev_b64 v[148:149], 2, v[148:149]
	v_lshl_add_u64 v[148:149], s[18:19], 0, v[148:149]
	global_load_dwordx4 v[238:241], v[148:149], off offset:-2048
	global_load_dwordx4 v[242:245], v[148:149], off offset:-1984
	global_load_dwordx4 v[246:249], v[148:149], off offset:-1536
	global_load_dwordx4 v[250:253], v[148:149], off offset:-1472
	s_waitcnt vmcnt(0)
.Llbv_skip:
	s_mov_b64 s[8:9], -1
	s_and_b64 vcc, exec, s[82:83]
	s_cbranch_vccz .LBB0_1556
	s_and_b64 vcc, exec, s[38:39]
	s_cbranch_vccz .LBB0_1553
	s_and_b64 vcc, exec, s[84:85]
	s_cbranch_vccz .LBB0_1550
	s_and_b64 vcc, exec, s[78:79]
	s_cbranch_vccz .LBB0_1547
	v_lshl_add_u64 v[148:149], s[46:47], 0, v[146:147]
	v_mov_b32_e32 v137, v144
	v_lshl_add_u64 v[148:149], v[136:137], 1, v[148:149]
	v_add_co_u32_e32 v148, vcc, 0xfffff000, v148
	v_cvt_pk_bf16_f32 v154, v124, v125
	v_cvt_pk_bf16_f32 v155, v126, v127
	s_mov_b64 s[8:9], 0
	s_nop 0
	v_addc_co_u32_e32 v149, vcc, -1, v149, vcc
	global_store_dwordx2 v[148:149], v[154:155], off offset:-1024

; __device__ __forceinline__ float sigmoidf_(float v) { return __builtin_amdgcn_rcpf(1.0f + __expf(-v)); }
; __device__ __forceinline__ float siluf_(float v) { return v * sigmoidf_(v); }
; __device__ __forceinline__ void store_bf16x4(bf16_t* p, f32x4 v) { u32x2 w; w.x = cvt_pk_bf16(v[0], v[1]); w.y = cvt_pk_bf16(v[2], v[3]); *(u32x2*)p = w; }
;   __device__ __forceinline__ void operator()(const f32x4 (&acc)[2][2][4][2], const pg8::Unit& u, int wr, int wc, int fr, int fq) const {
;     ...
;       if (pn < 2) { f32x4 o; for (int j = 0; j < 4; ++j) o[j] = siluf_(v[j]); store_bf16x4(QH + (size_t)row * 512 + col, o); }
;       else if (pn < 6) { const int c = col - 512; const f32x4 lb = *(const f32x4*)(LBj + c); f32x4 o; for (int j = 0; j < 4; ++j) o[j] = lb[j] + (1.f - lb[j]) * sigmoidf_(v[j]); *(f32x4*)(F + (size_t)row * 1024 + c) = o; }
.LBB0_1553:
	s_andn2_b64 vcc, exec, s[8:9]
	s_cbranch_vccnz .LBB0_1555
	v_ashrrev_i32_e32 v137, 31, v136
	v_lshlrev_b64 v[148:149], 2, v[136:137]
	v_mul_f32_e32 v137, 0xbfb8aa3b, v124
	v_exp_f32_e32 v137, v137
	v_sub_f32_e32 v163, 1.0, v239
	v_add_f32_e32 v137, 1.0, v137
	v_rcp_f32_e32 v158, v137
	v_mul_f32_e32 v137, 0xbfb8aa3b, v125
	v_exp_f32_e32 v137, v137
	v_sub_f32_e32 v162, 1.0, v238
	v_sub_f32_e32 v165, 1.0, v241
	v_sub_f32_e32 v164, 1.0, v240
	v_add_f32_e32 v137, 1.0, v137
	v_rcp_f32_e32 v159, v137
	v_mul_f32_e32 v137, 0xbfb8aa3b, v126
	v_exp_f32_e32 v137, v137
	v_pk_fma_f32 v[154:155], v[158:159], v[162:163], v[238:239]
	v_lshl_add_u64 v[158:159], s[20:21], 0, v[140:141]
	v_add_f32_e32 v137, 1.0, v137
	v_rcp_f32_e32 v160, v137
	v_mul_f32_e32 v137, 0xbfb8aa3b, v127
	v_exp_f32_e32 v137, v137
	v_lshl_add_u64 v[148:149], v[158:159], 0, v[148:149]
	v_add_f32_e32 v137, 1.0, v137
	v_rcp_f32_e32 v161, v137
	s_nop 0
	v_pk_fma_f32 v[156:157], v[160:161], v[164:165], v[240:241]
	global_store_dwordx4 v[148:149], v[154:157], off offset:-2048

; __device__ __forceinline__ float sigmoidf_(float v) { return __builtin_amdgcn_rcpf(1.0f + __expf(-v)); }
; __device__ __forceinline__ float siluf_(float v) { return v * sigmoidf_(v); }
; __device__ __forceinline__ void store_bf16x4(bf16_t* p, f32x4 v) { u32x2 w; w.x = cvt_pk_bf16(v[0], v[1]); w.y = cvt_pk_bf16(v[2], v[3]); *(u32x2*)p = w; }
;   __device__ __forceinline__ void operator()(const f32x4 (&acc)[2][2][4][2], const pg8::Unit& u, int wr, int wc, int fr, int fq) const {
;     ...
;       if (pn < 2) { f32x4 o; for (int j = 0; j < 4; ++j) o[j] = siluf_(v[j]); store_bf16x4(QH + (size_t)row * 512 + col, o); }
;       else if (pn < 6) { const int c = col - 512; const f32x4 lb = *(const f32x4*)(LBj + c); f32x4 o; for (int j = 0; j < 4; ++j) o[j] = lb[j] + (1.f - lb[j]) * sigmoidf_(v[j]); *(f32x4*)(F + (size_t)row * 1024 + c) = o; }
.LBB0_1569:
	s_andn2_b64 vcc, exec, s[24:25]
	s_cbranch_vccnz .LBB0_1571
	v_lshlrev_b64 v[154:155], 2, v[136:137]
	v_mul_f32_e32 v139, 0xbfb8aa3b, v120
	v_exp_f32_e32 v139, v139
	v_sub_f32_e32 v161, 1.0, v243
	v_add_f32_e32 v139, 1.0, v139
	v_rcp_f32_e32 v156, v139
	v_mul_f32_e32 v139, 0xbfb8aa3b, v121
	v_exp_f32_e32 v139, v139
	v_sub_f32_e32 v160, 1.0, v242
	v_sub_f32_e32 v163, 1.0, v245
	v_sub_f32_e32 v162, 1.0, v244
	v_add_f32_e32 v139, 1.0, v139
	v_rcp_f32_e32 v157, v139
	v_mul_f32_e32 v139, 0xbfb8aa3b, v122
	v_exp_f32_e32 v139, v139
	v_pk_fma_f32 v[124:125], v[156:157], v[160:161], v[242:243]
	v_lshl_add_u64 v[156:157], s[20:21], 0, v[140:141]
	v_add_f32_e32 v139, 1.0, v139
	v_rcp_f32_e32 v158, v139
	v_mul_f32_e32 v139, 0xbfb8aa3b, v123
	v_exp_f32_e32 v139, v139
	v_lshl_add_u64 v[154:155], v[156:157], 0, v[154:155]
	v_add_f32_e32 v139, 1.0, v139
	v_rcp_f32_e32 v159, v139
	s_nop 0
	v_pk_fma_f32 v[126:127], v[158:159], v[162:163], v[244:245]
	global_store_dwordx4 v[154:155], v[124:127], off offset:-1984

; __device__ __forceinline__ float sigmoidf_(float v) { return __builtin_amdgcn_rcpf(1.0f + __expf(-v)); }
; __device__ __forceinline__ float siluf_(float v) { return v * sigmoidf_(v); }
; __device__ __forceinline__ void store_bf16x4(bf16_t* p, f32x4 v) { u32x2 w; w.x = cvt_pk_bf16(v[0], v[1]); w.y = cvt_pk_bf16(v[2], v[3]); *(u32x2*)p = w; }
;   __device__ __forceinline__ void operator()(const f32x4 (&acc)[2][2][4][2], const pg8::Unit& u, int wr, int wc, int fr, int fq) const {
;     ...
;       if (pn < 2) { f32x4 o; for (int j = 0; j < 4; ++j) o[j] = siluf_(v[j]); store_bf16x4(QH + (size_t)row * 512 + col, o); }
;       else if (pn < 6) { const int c = col - 512; const f32x4 lb = *(const f32x4*)(LBj + c); f32x4 o; for (int j = 0; j < 4; ++j) o[j] = lb[j] + (1.f - lb[j]) * sigmoidf_(v[j]); *(f32x4*)(F + (size_t)row * 1024 + c) = o; }
.LBB0_1583:
	s_andn2_b64 vcc, exec, s[24:25]
	s_cbranch_vccnz .LBB0_1585
	v_lshlrev_b64 v[124:125], 2, v[136:137]
	v_mul_f32_e32 v139, 0xbfb8aa3b, v118
	v_exp_f32_e32 v139, v139
	v_mul_f32_e32 v126, 0xbfb8aa3b, v116
	v_mul_f32_e32 v127, 0xbfb8aa3b, v117
	v_exp_f32_e32 v126, v126
	v_add_f32_e32 v139, 1.0, v139
	v_exp_f32_e32 v127, v127
	v_rcp_f32_e32 v154, v139
	v_mul_f32_e32 v139, 0xbfb8aa3b, v119
	v_exp_f32_e32 v139, v139
	v_add_f32_e32 v126, 1.0, v126
	v_add_f32_e32 v127, 1.0, v127
	v_rcp_f32_e32 v126, v126
	v_rcp_f32_e32 v127, v127
	v_add_f32_e32 v139, 1.0, v139
	v_rcp_f32_e32 v155, v139
	v_sub_f32_e32 v157, 1.0, v247
	v_sub_f32_e32 v156, 1.0, v246
	v_sub_f32_e32 v159, 1.0, v249
	v_sub_f32_e32 v158, 1.0, v248
	v_pk_fma_f32 v[120:121], v[126:127], v[156:157], v[246:247]
	v_lshl_add_u64 v[126:127], s[20:21], 0, v[140:141]
	v_pk_fma_f32 v[122:123], v[154:155], v[158:159], v[248:249]
	v_lshl_add_u64 v[124:125], v[126:127], 0, v[124:125]
	global_store_dwordx4 v[124:125], v[120:123], off offset:-1536

; __device__ __forceinline__ float sigmoidf_(float v) { return __builtin_amdgcn_rcpf(1.0f + __expf(-v)); }
; __device__ __forceinline__ float siluf_(float v) { return v * sigmoidf_(v); }
; __device__ __forceinline__ void store_bf16x4(bf16_t* p, f32x4 v) { u32x2 w; w.x = cvt_pk_bf16(v[0], v[1]); w.y = cvt_pk_bf16(v[2], v[3]); *(u32x2*)p = w; }
;   __device__ __forceinline__ void operator()(const f32x4 (&acc)[2][2][4][2], const pg8::Unit& u, int wr, int wc, int fr, int fq) const {
;     ...
;       if (pn < 2) { f32x4 o; for (int j = 0; j < 4; ++j) o[j] = siluf_(v[j]); store_bf16x4(QH + (size_t)row * 512 + col, o); }
;       else if (pn < 6) { const int c = col - 512; const f32x4 lb = *(const f32x4*)(LBj + c); f32x4 o; for (int j = 0; j < 4; ++j) o[j] = lb[j] + (1.f - lb[j]) * sigmoidf_(v[j]); *(f32x4*)(F + (size_t)row * 1024 + c) = o; }
.LBB0_1597:
	s_andn2_b64 vcc, exec, s[24:25]
	s_cbranch_vccnz .LBB0_1599
	v_lshlrev_b64 v[120:121], 2, v[136:137]
	v_mul_f32_e32 v124, 0xbfb8aa3b, v112
	v_mul_f32_e32 v125, 0xbfb8aa3b, v113
	v_mul_f32_e32 v126, 0xbfb8aa3b, v114
	v_mul_f32_e32 v127, 0xbfb8aa3b, v115
	v_exp_f32_e32 v124, v124
	v_exp_f32_e32 v125, v125
	v_exp_f32_e32 v126, v126
	v_exp_f32_e32 v127, v127
	v_add_f32_e32 v124, 1.0, v124
	v_add_f32_e32 v125, 1.0, v125
	v_add_f32_e32 v126, 1.0, v126
	v_add_f32_e32 v127, 1.0, v127
	v_rcp_f32_e32 v124, v124
	v_rcp_f32_e32 v125, v125
	v_rcp_f32_e32 v126, v126
	v_rcp_f32_e32 v127, v127
	v_lshl_add_u64 v[122:123], s[20:21], 0, v[140:141]
	v_lshl_add_u64 v[120:121], v[122:123], 0, v[120:121]
	v_sub_f32_e32 v141, 1.0, v251
	v_sub_f32_e32 v140, 1.0, v250
	v_sub_f32_e32 v143, 1.0, v253
	v_sub_f32_e32 v142, 1.0, v252
	v_pk_fma_f32 v[118:119], v[126:127], v[142:143], v[252:253]
	v_pk_fma_f32 v[116:117], v[124:125], v[140:141], v[250:251]
	global_store_dwordx4 v[120:121], v[116:119], off offset:-1472

; __device__ __forceinline__ float sigmoidf_(float v) { return __builtin_amdgcn_rcpf(1.0f + __expf(-v)); }
; __device__ __forceinline__ float siluf_(float v) { return v * sigmoidf_(v); }
; __device__ __forceinline__ void store_bf16x4(bf16_t* p, f32x4 v) { u32x2 w; w.x = cvt_pk_bf16(v[0], v[1]); w.y = cvt_pk_bf16(v[2], v[3]); *(u32x2*)p = w; }
;   __device__ __forceinline__ void operator()(const f32x4 (&acc)[2][2][4][2], const pg8::Unit& u, int wr, int wc, int fr, int fq) const {
;     ...
;       if (pn < 2) { f32x4 o; for (int j = 0; j < 4; ++j) o[j] = siluf_(v[j]); store_bf16x4(QH + (size_t)row * 512 + col, o); }
;       else if (pn < 6) { const int c = col - 512; const f32x4 lb = *(const f32x4*)(LBj + c); f32x4 o; for (int j = 0; j < 4; ++j) o[j] = lb[j] + (1.f - lb[j]) * sigmoidf_(v[j]); *(f32x4*)(F + (size_t)row * 1024 + c) = o; }
.LBB0_1617:
	s_andn2_b64 vcc, exec, s[24:25]
	s_cbranch_vccnz .LBB0_1619
	v_lshlrev_b64 v[122:123], 2, v[136:137]
	v_mul_f32_e32 v124, 0xbfb8aa3b, v108
	v_mul_f32_e32 v125, 0xbfb8aa3b, v109
	v_exp_f32_e32 v124, v124
	v_exp_f32_e32 v125, v125
	v_mul_f32_e32 v126, 0xbfb8aa3b, v110
	v_mul_f32_e32 v127, 0xbfb8aa3b, v111
	v_exp_f32_e32 v126, v126
	v_exp_f32_e32 v127, v127
	v_add_f32_e32 v124, 1.0, v124
	v_add_f32_e32 v125, 1.0, v125
	v_rcp_f32_e32 v124, v124
	v_rcp_f32_e32 v125, v125
	v_add_f32_e32 v126, 1.0, v126
	v_add_f32_e32 v127, 1.0, v127
	v_rcp_f32_e32 v126, v126
	v_rcp_f32_e32 v127, v127
	v_sub_f32_e32 v141, 1.0, v239
	v_sub_f32_e32 v140, 1.0, v238
	v_sub_f32_e32 v143, 1.0, v241
	v_sub_f32_e32 v142, 1.0, v240
	v_pk_fma_f32 v[118:119], v[124:125], v[140:141], v[238:239]
	v_lshl_add_u64 v[124:125], s[20:21], 0, v[112:113]
	v_pk_fma_f32 v[120:121], v[126:127], v[142:143], v[240:241]
	v_lshl_add_u64 v[122:123], v[124:125], 0, v[122:123]
	global_store_dwordx4 v[122:123], v[118:121], off offset:-2048

; __device__ __forceinline__ float sigmoidf_(float v) { return __builtin_amdgcn_rcpf(1.0f + __expf(-v)); }
; __device__ __forceinline__ float siluf_(float v) { return v * sigmoidf_(v); }
; __device__ __forceinline__ void store_bf16x4(bf16_t* p, f32x4 v) { u32x2 w; w.x = cvt_pk_bf16(v[0], v[1]); w.y = cvt_pk_bf16(v[2], v[3]); *(u32x2*)p = w; }
;   __device__ __forceinline__ void operator()(const f32x4 (&acc)[2][2][4][2], const pg8::Unit& u, int wr, int wc, int fr, int fq) const {
;     ...
;       if (pn < 2) { f32x4 o; for (int j = 0; j < 4; ++j) o[j] = siluf_(v[j]); store_bf16x4(QH + (size_t)row * 512 + col, o); }
;       else if (pn < 6) { const int c = col - 512; const f32x4 lb = *(const f32x4*)(LBj + c); f32x4 o; for (int j = 0; j < 4; ++j) o[j] = lb[j] + (1.f - lb[j]) * sigmoidf_(v[j]); *(f32x4*)(F + (size_t)row * 1024 + c) = o; }
.LBB0_1631:
	s_andn2_b64 vcc, exec, s[24:25]
	s_cbranch_vccnz .LBB0_1633
	v_lshlrev_b64 v[120:121], 2, v[136:137]
	v_mul_f32_e32 v122, 0xbfb8aa3b, v104
	v_mul_f32_e32 v123, 0xbfb8aa3b, v105
	v_exp_f32_e32 v122, v122
	v_exp_f32_e32 v123, v123
	v_mul_f32_e32 v124, 0xbfb8aa3b, v106
	v_mul_f32_e32 v125, 0xbfb8aa3b, v107
	v_exp_f32_e32 v124, v124
	v_exp_f32_e32 v125, v125
	v_add_f32_e32 v122, 1.0, v122
	v_add_f32_e32 v123, 1.0, v123
	v_rcp_f32_e32 v122, v122
	v_rcp_f32_e32 v123, v123
	v_add_f32_e32 v124, 1.0, v124
	v_add_f32_e32 v125, 1.0, v125
	v_rcp_f32_e32 v124, v124
	v_rcp_f32_e32 v125, v125
	v_sub_f32_e32 v127, 1.0, v243
	v_sub_f32_e32 v126, 1.0, v242
	v_sub_f32_e32 v141, 1.0, v245
	v_sub_f32_e32 v140, 1.0, v244
	v_pk_fma_f32 v[108:109], v[122:123], v[126:127], v[242:243]
	v_lshl_add_u64 v[122:123], s[20:21], 0, v[112:113]
	v_pk_fma_f32 v[110:111], v[124:125], v[140:141], v[244:245]
	v_lshl_add_u64 v[120:121], v[122:123], 0, v[120:121]
	global_store_dwordx4 v[120:121], v[108:111], off offset:-1984

; __device__ __forceinline__ float sigmoidf_(float v) { return __builtin_amdgcn_rcpf(1.0f + __expf(-v)); }
; __device__ __forceinline__ float siluf_(float v) { return v * sigmoidf_(v); }
; __device__ __forceinline__ void store_bf16x4(bf16_t* p, f32x4 v) { u32x2 w; w.x = cvt_pk_bf16(v[0], v[1]); w.y = cvt_pk_bf16(v[2], v[3]); *(u32x2*)p = w; }
;   __device__ __forceinline__ void operator()(const f32x4 (&acc)[2][2][4][2], const pg8::Unit& u, int wr, int wc, int fr, int fq) const {
;     ...
;       if (pn < 2) { f32x4 o; for (int j = 0; j < 4; ++j) o[j] = siluf_(v[j]); store_bf16x4(QH + (size_t)row * 512 + col, o); }
;       else if (pn < 6) { const int c = col - 512; const f32x4 lb = *(const f32x4*)(LBj + c); f32x4 o; for (int j = 0; j < 4; ++j) o[j] = lb[j] + (1.f - lb[j]) * sigmoidf_(v[j]); *(f32x4*)(F + (size_t)row * 1024 + c) = o; }
.LBB0_1645:
	s_andn2_b64 vcc, exec, s[24:25]
	s_cbranch_vccnz .LBB0_1647
	v_lshlrev_b64 v[108:109], 2, v[136:137]
	v_mul_f32_e32 v110, 0xbfb8aa3b, v100
	v_mul_f32_e32 v111, 0xbfb8aa3b, v101
	v_exp_f32_e32 v110, v110
	v_exp_f32_e32 v111, v111
	v_mul_f32_e32 v120, 0xbfb8aa3b, v102
	v_mul_f32_e32 v121, 0xbfb8aa3b, v103
	v_exp_f32_e32 v120, v120
	v_exp_f32_e32 v121, v121
	v_add_f32_e32 v110, 1.0, v110
	v_add_f32_e32 v111, 1.0, v111
	v_rcp_f32_e32 v110, v110
	v_rcp_f32_e32 v111, v111
	v_add_f32_e32 v120, 1.0, v120
	v_add_f32_e32 v121, 1.0, v121
	v_rcp_f32_e32 v120, v120
	v_rcp_f32_e32 v121, v121
	v_sub_f32_e32 v123, 1.0, v247
	v_sub_f32_e32 v122, 1.0, v246
	v_sub_f32_e32 v125, 1.0, v249
	v_sub_f32_e32 v124, 1.0, v248
	v_pk_fma_f32 v[104:105], v[110:111], v[122:123], v[246:247]
	v_lshl_add_u64 v[110:111], s[20:21], 0, v[112:113]
	v_pk_fma_f32 v[106:107], v[120:121], v[124:125], v[248:249]
	v_lshl_add_u64 v[108:109], v[110:111], 0, v[108:109]
	global_store_dwordx4 v[108:109], v[104:107], off offset:-1536

; __device__ __forceinline__ float sigmoidf_(float v) { return __builtin_amdgcn_rcpf(1.0f + __expf(-v)); }
; __device__ __forceinline__ float siluf_(float v) { return v * sigmoidf_(v); }
; __device__ __forceinline__ void store_bf16x4(bf16_t* p, f32x4 v) { u32x2 w; w.x = cvt_pk_bf16(v[0], v[1]); w.y = cvt_pk_bf16(v[2], v[3]); *(u32x2*)p = w; }
;   __device__ __forceinline__ void operator()(const f32x4 (&acc)[2][2][4][2], const pg8::Unit& u, int wr, int wc, int fr, int fq) const {
;     ...
;       if (pn < 2) { f32x4 o; for (int j = 0; j < 4; ++j) o[j] = siluf_(v[j]); store_bf16x4(QH + (size_t)row * 512 + col, o); }
;       else if (pn < 6) { const int c = col - 512; const f32x4 lb = *(const f32x4*)(LBj + c); f32x4 o; for (int j = 0; j < 4; ++j) o[j] = lb[j] + (1.f - lb[j]) * sigmoidf_(v[j]); *(f32x4*)(F + (size_t)row * 1024 + c) = o; }
.LBB0_1659:
	s_andn2_b64 vcc, exec, s[24:25]
	s_cbranch_vccnz .LBB0_1661
	v_lshlrev_b64 v[104:105], 2, v[136:137]
	v_mul_f32_e32 v108, 0xbfb8aa3b, v96
	v_mul_f32_e32 v109, 0xbfb8aa3b, v97
	v_mul_f32_e32 v110, 0xbfb8aa3b, v98
	v_mul_f32_e32 v111, 0xbfb8aa3b, v99
	v_exp_f32_e32 v108, v108
	v_exp_f32_e32 v109, v109
	v_exp_f32_e32 v110, v110
	v_exp_f32_e32 v111, v111
	v_add_f32_e32 v108, 1.0, v108
	v_add_f32_e32 v109, 1.0, v109
	v_add_f32_e32 v110, 1.0, v110
	v_add_f32_e32 v111, 1.0, v111
	v_rcp_f32_e32 v108, v108
	v_rcp_f32_e32 v109, v109
	v_rcp_f32_e32 v110, v110
	v_rcp_f32_e32 v111, v111
	v_lshl_add_u64 v[106:107], s[20:21], 0, v[112:113]
	v_lshl_add_u64 v[104:105], v[106:107], 0, v[104:105]
	v_sub_f32_e32 v113, 1.0, v251
	v_sub_f32_e32 v112, 1.0, v250
	v_sub_f32_e32 v115, 1.0, v253
	v_sub_f32_e32 v114, 1.0, v252
	v_pk_fma_f32 v[102:103], v[110:111], v[114:115], v[252:253]
	v_pk_fma_f32 v[100:101], v[108:109], v[112:113], v[250:251]
	global_store_dwordx4 v[104:105], v[100:103], off offset:-1472

; __device__ __forceinline__ float sigmoidf_(float v) { return __builtin_amdgcn_rcpf(1.0f + __expf(-v)); }
; __device__ __forceinline__ float siluf_(float v) { return v * sigmoidf_(v); }
; __device__ __forceinline__ void store_bf16x4(bf16_t* p, f32x4 v) { u32x2 w; w.x = cvt_pk_bf16(v[0], v[1]); w.y = cvt_pk_bf16(v[2], v[3]); *(u32x2*)p = w; }
;   __device__ __forceinline__ void operator()(const f32x4 (&acc)[2][2][4][2], const pg8::Unit& u, int wr, int wc, int fr, int fq) const {
;     ...
;       if (pn < 2) { f32x4 o; for (int j = 0; j < 4; ++j) o[j] = siluf_(v[j]); store_bf16x4(QH + (size_t)row * 512 + col, o); }
;       else if (pn < 6) { const int c = col - 512; const f32x4 lb = *(const f32x4*)(LBj + c); f32x4 o; for (int j = 0; j < 4; ++j) o[j] = lb[j] + (1.f - lb[j]) * sigmoidf_(v[j]); *(f32x4*)(F + (size_t)row * 1024 + c) = o; }
.LBB0_1681:
	s_andn2_b64 vcc, exec, s[24:25]
	s_cbranch_vccnz .LBB0_1683
	v_lshlrev_b64 v[106:107], 2, v[136:137]
	v_mul_f32_e32 v108, 0xbfb8aa3b, v92
	v_mul_f32_e32 v109, 0xbfb8aa3b, v93
	v_exp_f32_e32 v108, v108
	v_exp_f32_e32 v109, v109
	v_mul_f32_e32 v110, 0xbfb8aa3b, v94
	v_mul_f32_e32 v111, 0xbfb8aa3b, v95
	v_exp_f32_e32 v110, v110
	v_exp_f32_e32 v111, v111
	v_add_f32_e32 v108, 1.0, v108
	v_add_f32_e32 v109, 1.0, v109
	v_rcp_f32_e32 v108, v108
	v_rcp_f32_e32 v109, v109
	v_add_f32_e32 v110, 1.0, v110
	v_add_f32_e32 v111, 1.0, v111
	v_rcp_f32_e32 v110, v110
	v_rcp_f32_e32 v111, v111
	v_sub_f32_e32 v113, 1.0, v239
	v_sub_f32_e32 v112, 1.0, v238
	v_sub_f32_e32 v115, 1.0, v241
	v_sub_f32_e32 v114, 1.0, v240
	v_pk_fma_f32 v[102:103], v[108:109], v[112:113], v[238:239]
	v_lshl_add_u64 v[108:109], s[20:21], 0, v[96:97]
	v_pk_fma_f32 v[104:105], v[110:111], v[114:115], v[240:241]
	v_lshl_add_u64 v[106:107], v[108:109], 0, v[106:107]
	global_store_dwordx4 v[106:107], v[102:105], off offset:-2048

; __device__ __forceinline__ float sigmoidf_(float v) { return __builtin_amdgcn_rcpf(1.0f + __expf(-v)); }
; __device__ __forceinline__ float siluf_(float v) { return v * sigmoidf_(v); }
; __device__ __forceinline__ void store_bf16x4(bf16_t* p, f32x4 v) { u32x2 w; w.x = cvt_pk_bf16(v[0], v[1]); w.y = cvt_pk_bf16(v[2], v[3]); *(u32x2*)p = w; }
;   __device__ __forceinline__ void operator()(const f32x4 (&acc)[2][2][4][2], const pg8::Unit& u, int wr, int wc, int fr, int fq) const {
;     ...
;       if (pn < 2) { f32x4 o; for (int j = 0; j < 4; ++j) o[j] = siluf_(v[j]); store_bf16x4(QH + (size_t)row * 512 + col, o); }
;       else if (pn < 6) { const int c = col - 512; const f32x4 lb = *(const f32x4*)(LBj + c); f32x4 o; for (int j = 0; j < 4; ++j) o[j] = lb[j] + (1.f - lb[j]) * sigmoidf_(v[j]); *(f32x4*)(F + (size_t)row * 1024 + c) = o; }
.LBB0_1695:
	s_andn2_b64 vcc, exec, s[24:25]
	s_cbranch_vccnz .LBB0_1697
	v_lshlrev_b64 v[104:105], 2, v[136:137]
	v_mul_f32_e32 v106, 0xbfb8aa3b, v88
	v_mul_f32_e32 v107, 0xbfb8aa3b, v89
	v_exp_f32_e32 v106, v106
	v_exp_f32_e32 v107, v107
	v_mul_f32_e32 v108, 0xbfb8aa3b, v90
	v_mul_f32_e32 v109, 0xbfb8aa3b, v91
	v_exp_f32_e32 v108, v108
	v_exp_f32_e32 v109, v109
	v_add_f32_e32 v106, 1.0, v106
	v_add_f32_e32 v107, 1.0, v107
	v_rcp_f32_e32 v106, v106
	v_rcp_f32_e32 v107, v107
	v_add_f32_e32 v108, 1.0, v108
	v_add_f32_e32 v109, 1.0, v109
	v_rcp_f32_e32 v108, v108
	v_rcp_f32_e32 v109, v109
	v_sub_f32_e32 v111, 1.0, v243
	v_sub_f32_e32 v110, 1.0, v242
	v_sub_f32_e32 v113, 1.0, v245
	v_sub_f32_e32 v112, 1.0, v244
	v_pk_fma_f32 v[92:93], v[106:107], v[110:111], v[242:243]
	v_lshl_add_u64 v[106:107], s[20:21], 0, v[96:97]
	v_pk_fma_f32 v[94:95], v[108:109], v[112:113], v[244:245]
	v_lshl_add_u64 v[104:105], v[106:107], 0, v[104:105]
	global_store_dwordx4 v[104:105], v[92:95], off offset:-1984

; __device__ __forceinline__ float sigmoidf_(float v) { return __builtin_amdgcn_rcpf(1.0f + __expf(-v)); }
; __device__ __forceinline__ float siluf_(float v) { return v * sigmoidf_(v); }
; __device__ __forceinline__ void store_bf16x4(bf16_t* p, f32x4 v) { u32x2 w; w.x = cvt_pk_bf16(v[0], v[1]); w.y = cvt_pk_bf16(v[2], v[3]); *(u32x2*)p = w; }
;   __device__ __forceinline__ void operator()(const f32x4 (&acc)[2][2][4][2], const pg8::Unit& u, int wr, int wc, int fr, int fq) const {
;     ...
;       if (pn < 2) { f32x4 o; for (int j = 0; j < 4; ++j) o[j] = siluf_(v[j]); store_bf16x4(QH + (size_t)row * 512 + col, o); }
;       else if (pn < 6) { const int c = col - 512; const f32x4 lb = *(const f32x4*)(LBj + c); f32x4 o; for (int j = 0; j < 4; ++j) o[j] = lb[j] + (1.f - lb[j]) * sigmoidf_(v[j]); *(f32x4*)(F + (size_t)row * 1024 + c) = o; }
.LBB0_1709:
	s_andn2_b64 vcc, exec, s[24:25]
	s_cbranch_vccnz .LBB0_1711
	v_lshlrev_b64 v[92:93], 2, v[136:137]
	v_mul_f32_e32 v94, 0xbfb8aa3b, v84
	v_mul_f32_e32 v95, 0xbfb8aa3b, v85
	v_exp_f32_e32 v94, v94
	v_exp_f32_e32 v95, v95
	v_mul_f32_e32 v104, 0xbfb8aa3b, v86
	v_mul_f32_e32 v105, 0xbfb8aa3b, v87
	v_exp_f32_e32 v104, v104
	v_exp_f32_e32 v105, v105
	v_add_f32_e32 v94, 1.0, v94
	v_add_f32_e32 v95, 1.0, v95
	v_rcp_f32_e32 v94, v94
	v_rcp_f32_e32 v95, v95
	v_add_f32_e32 v104, 1.0, v104
	v_add_f32_e32 v105, 1.0, v105
	v_rcp_f32_e32 v104, v104
	v_rcp_f32_e32 v105, v105
	v_sub_f32_e32 v107, 1.0, v247
	v_sub_f32_e32 v106, 1.0, v246
	v_sub_f32_e32 v109, 1.0, v249
	v_sub_f32_e32 v108, 1.0, v248
	v_pk_fma_f32 v[88:89], v[94:95], v[106:107], v[246:247]
	v_lshl_add_u64 v[94:95], s[20:21], 0, v[96:97]
	v_pk_fma_f32 v[90:91], v[104:105], v[108:109], v[248:249]
	v_lshl_add_u64 v[92:93], v[94:95], 0, v[92:93]
	global_store_dwordx4 v[92:93], v[88:91], off offset:-1536

; __device__ __forceinline__ float sigmoidf_(float v) { return __builtin_amdgcn_rcpf(1.0f + __expf(-v)); }
; __device__ __forceinline__ float siluf_(float v) { return v * sigmoidf_(v); }
; __device__ __forceinline__ void store_bf16x4(bf16_t* p, f32x4 v) { u32x2 w; w.x = cvt_pk_bf16(v[0], v[1]); w.y = cvt_pk_bf16(v[2], v[3]); *(u32x2*)p = w; }
;   __device__ __forceinline__ void operator()(const f32x4 (&acc)[2][2][4][2], const pg8::Unit& u, int wr, int wc, int fr, int fq) const {
;     ...
;       if (pn < 2) { f32x4 o; for (int j = 0; j < 4; ++j) o[j] = siluf_(v[j]); store_bf16x4(QH + (size_t)row * 512 + col, o); }
;       else if (pn < 6) { const int c = col - 512; const f32x4 lb = *(const f32x4*)(LBj + c); f32x4 o; for (int j = 0; j < 4; ++j) o[j] = lb[j] + (1.f - lb[j]) * sigmoidf_(v[j]); *(f32x4*)(F + (size_t)row * 1024 + c) = o; }
.LBB0_1723:
	s_andn2_b64 vcc, exec, s[24:25]
	s_cbranch_vccnz .LBB0_1725
	v_lshlrev_b64 v[88:89], 2, v[136:137]
	v_mul_f32_e32 v92, 0xbfb8aa3b, v80
	v_mul_f32_e32 v93, 0xbfb8aa3b, v81
	v_mul_f32_e32 v94, 0xbfb8aa3b, v82
	v_mul_f32_e32 v95, 0xbfb8aa3b, v83
	v_exp_f32_e32 v92, v92
	v_exp_f32_e32 v93, v93
	v_exp_f32_e32 v94, v94
	v_exp_f32_e32 v95, v95
	v_add_f32_e32 v92, 1.0, v92
	v_add_f32_e32 v93, 1.0, v93
	v_add_f32_e32 v94, 1.0, v94
	v_add_f32_e32 v95, 1.0, v95
	v_rcp_f32_e32 v92, v92
	v_rcp_f32_e32 v93, v93
	v_rcp_f32_e32 v94, v94
	v_rcp_f32_e32 v95, v95
	v_lshl_add_u64 v[90:91], s[20:21], 0, v[96:97]
	v_lshl_add_u64 v[88:89], v[90:91], 0, v[88:89]
	v_sub_f32_e32 v97, 1.0, v251
	v_sub_f32_e32 v96, 1.0, v250
	v_sub_f32_e32 v99, 1.0, v253
	v_sub_f32_e32 v98, 1.0, v252
	v_pk_fma_f32 v[86:87], v[94:95], v[98:99], v[252:253]
	v_pk_fma_f32 v[84:85], v[92:93], v[96:97], v[250:251]
	global_store_dwordx4 v[88:89], v[84:87], off offset:-1472

; __device__ __forceinline__ float sigmoidf_(float v) { return __builtin_amdgcn_rcpf(1.0f + __expf(-v)); }
; __device__ __forceinline__ float siluf_(float v) { return v * sigmoidf_(v); }
; __device__ __forceinline__ void store_bf16x4(bf16_t* p, f32x4 v) { u32x2 w; w.x = cvt_pk_bf16(v[0], v[1]); w.y = cvt_pk_bf16(v[2], v[3]); *(u32x2*)p = w; }
;   __device__ __forceinline__ void operator()(const f32x4 (&acc)[2][2][4][2], const pg8::Unit& u, int wr, int wc, int fr, int fq) const {
;     ...
;       if (pn < 2) { f32x4 o; for (int j = 0; j < 4; ++j) o[j] = siluf_(v[j]); store_bf16x4(QH + (size_t)row * 512 + col, o); }
;       else if (pn < 6) { const int c = col - 512; const f32x4 lb = *(const f32x4*)(LBj + c); f32x4 o; for (int j = 0; j < 4; ++j) o[j] = lb[j] + (1.f - lb[j]) * sigmoidf_(v[j]); *(f32x4*)(F + (size_t)row * 1024 + c) = o; }
.LBB0_1745:
	s_andn2_b64 vcc, exec, s[24:25]
	s_cbranch_vccnz .LBB0_1747
	v_lshlrev_b64 v[90:91], 2, v[136:137]
	v_mul_f32_e32 v92, 0xbfb8aa3b, v76
	v_mul_f32_e32 v93, 0xbfb8aa3b, v77
	v_exp_f32_e32 v92, v92
	v_exp_f32_e32 v93, v93
	v_mul_f32_e32 v94, 0xbfb8aa3b, v78
	v_mul_f32_e32 v95, 0xbfb8aa3b, v79
	v_exp_f32_e32 v94, v94
	v_exp_f32_e32 v95, v95
	v_add_f32_e32 v92, 1.0, v92
	v_add_f32_e32 v93, 1.0, v93
	v_rcp_f32_e32 v92, v92
	v_rcp_f32_e32 v93, v93
	v_add_f32_e32 v94, 1.0, v94
	v_add_f32_e32 v95, 1.0, v95
	v_rcp_f32_e32 v94, v94
	v_rcp_f32_e32 v95, v95
	v_sub_f32_e32 v97, 1.0, v239
	v_sub_f32_e32 v96, 1.0, v238
	v_sub_f32_e32 v99, 1.0, v241
	v_sub_f32_e32 v98, 1.0, v240
	v_pk_fma_f32 v[86:87], v[92:93], v[96:97], v[238:239]
	v_lshl_add_u64 v[92:93], s[20:21], 0, v[80:81]
	v_pk_fma_f32 v[88:89], v[94:95], v[98:99], v[240:241]
	v_lshl_add_u64 v[90:91], v[92:93], 0, v[90:91]
	global_store_dwordx4 v[90:91], v[86:89], off offset:-2048

; __device__ __forceinline__ float sigmoidf_(float v) { return __builtin_amdgcn_rcpf(1.0f + __expf(-v)); }
; __device__ __forceinline__ float siluf_(float v) { return v * sigmoidf_(v); }
; __device__ __forceinline__ void store_bf16x4(bf16_t* p, f32x4 v) { u32x2 w; w.x = cvt_pk_bf16(v[0], v[1]); w.y = cvt_pk_bf16(v[2], v[3]); *(u32x2*)p = w; }
;   __device__ __forceinline__ void operator()(const f32x4 (&acc)[2][2][4][2], const pg8::Unit& u, int wr, int wc, int fr, int fq) const {
;     ...
;       if (pn < 2) { f32x4 o; for (int j = 0; j < 4; ++j) o[j] = siluf_(v[j]); store_bf16x4(QH + (size_t)row * 512 + col, o); }
;       else if (pn < 6) { const int c = col - 512; const f32x4 lb = *(const f32x4*)(LBj + c); f32x4 o; for (int j = 0; j < 4; ++j) o[j] = lb[j] + (1.f - lb[j]) * sigmoidf_(v[j]); *(f32x4*)(F + (size_t)row * 1024 + c) = o; }
.LBB0_1759:
	s_andn2_b64 vcc, exec, s[24:25]
	s_cbranch_vccnz .LBB0_1761
	v_lshlrev_b64 v[88:89], 2, v[136:137]
	v_mul_f32_e32 v90, 0xbfb8aa3b, v72
	v_mul_f32_e32 v91, 0xbfb8aa3b, v73
	v_exp_f32_e32 v90, v90
	v_exp_f32_e32 v91, v91
	v_mul_f32_e32 v92, 0xbfb8aa3b, v74
	v_mul_f32_e32 v93, 0xbfb8aa3b, v75
	v_exp_f32_e32 v92, v92
	v_exp_f32_e32 v93, v93
	v_add_f32_e32 v90, 1.0, v90
	v_add_f32_e32 v91, 1.0, v91
	v_rcp_f32_e32 v90, v90
	v_rcp_f32_e32 v91, v91
	v_add_f32_e32 v92, 1.0, v92
	v_add_f32_e32 v93, 1.0, v93
	v_rcp_f32_e32 v92, v92
	v_rcp_f32_e32 v93, v93
	v_sub_f32_e32 v95, 1.0, v243
	v_sub_f32_e32 v94, 1.0, v242
	v_sub_f32_e32 v97, 1.0, v245
	v_sub_f32_e32 v96, 1.0, v244
	v_pk_fma_f32 v[76:77], v[90:91], v[94:95], v[242:243]
	v_lshl_add_u64 v[90:91], s[20:21], 0, v[80:81]
	v_pk_fma_f32 v[78:79], v[92:93], v[96:97], v[244:245]
	v_lshl_add_u64 v[88:89], v[90:91], 0, v[88:89]
	global_store_dwordx4 v[88:89], v[76:79], off offset:-1984

; __device__ __forceinline__ float sigmoidf_(float v) { return __builtin_amdgcn_rcpf(1.0f + __expf(-v)); }
; __device__ __forceinline__ float siluf_(float v) { return v * sigmoidf_(v); }
; __device__ __forceinline__ void store_bf16x4(bf16_t* p, f32x4 v) { u32x2 w; w.x = cvt_pk_bf16(v[0], v[1]); w.y = cvt_pk_bf16(v[2], v[3]); *(u32x2*)p = w; }
;   __device__ __forceinline__ void operator()(const f32x4 (&acc)[2][2][4][2], const pg8::Unit& u, int wr, int wc, int fr, int fq) const {
;     ...
;       if (pn < 2) { f32x4 o; for (int j = 0; j < 4; ++j) o[j] = siluf_(v[j]); store_bf16x4(QH + (size_t)row * 512 + col, o); }
;       else if (pn < 6) { const int c = col - 512; const f32x4 lb = *(const f32x4*)(LBj + c); f32x4 o; for (int j = 0; j < 4; ++j) o[j] = lb[j] + (1.f - lb[j]) * sigmoidf_(v[j]); *(f32x4*)(F + (size_t)row * 1024 + c) = o; }
.LBB0_1773:
	s_andn2_b64 vcc, exec, s[24:25]
	s_cbranch_vccnz .LBB0_1775
	v_lshlrev_b64 v[76:77], 2, v[136:137]
	v_mul_f32_e32 v78, 0xbfb8aa3b, v68
	v_mul_f32_e32 v79, 0xbfb8aa3b, v69
	v_exp_f32_e32 v78, v78
	v_exp_f32_e32 v79, v79
	v_mul_f32_e32 v88, 0xbfb8aa3b, v70
	v_mul_f32_e32 v89, 0xbfb8aa3b, v71
	v_exp_f32_e32 v88, v88
	v_exp_f32_e32 v89, v89
	v_add_f32_e32 v78, 1.0, v78
	v_add_f32_e32 v79, 1.0, v79
	v_rcp_f32_e32 v78, v78
	v_rcp_f32_e32 v79, v79
	v_add_f32_e32 v88, 1.0, v88
	v_add_f32_e32 v89, 1.0, v89
	v_rcp_f32_e32 v88, v88
	v_rcp_f32_e32 v89, v89
	v_sub_f32_e32 v91, 1.0, v247
	v_sub_f32_e32 v90, 1.0, v246
	v_sub_f32_e32 v93, 1.0, v249
	v_sub_f32_e32 v92, 1.0, v248
	v_pk_fma_f32 v[72:73], v[78:79], v[90:91], v[246:247]
	v_lshl_add_u64 v[78:79], s[20:21], 0, v[80:81]
	v_pk_fma_f32 v[74:75], v[88:89], v[92:93], v[248:249]
	v_lshl_add_u64 v[76:77], v[78:79], 0, v[76:77]
	global_store_dwordx4 v[76:77], v[72:75], off offset:-1536

; __device__ __forceinline__ float sigmoidf_(float v) { return __builtin_amdgcn_rcpf(1.0f + __expf(-v)); }
; __device__ __forceinline__ float siluf_(float v) { return v * sigmoidf_(v); }
; __device__ __forceinline__ void store_bf16x4(bf16_t* p, f32x4 v) { u32x2 w; w.x = cvt_pk_bf16(v[0], v[1]); w.y = cvt_pk_bf16(v[2], v[3]); *(u32x2*)p = w; }
;   __device__ __forceinline__ void operator()(const f32x4 (&acc)[2][2][4][2], const pg8::Unit& u, int wr, int wc, int fr, int fq) const {
;     ...
;       if (pn < 2) { f32x4 o; for (int j = 0; j < 4; ++j) o[j] = siluf_(v[j]); store_bf16x4(QH + (size_t)row * 512 + col, o); }
;       else if (pn < 6) { const int c = col - 512; const f32x4 lb = *(const f32x4*)(LBj + c); f32x4 o; for (int j = 0; j < 4; ++j) o[j] = lb[j] + (1.f - lb[j]) * sigmoidf_(v[j]); *(f32x4*)(F + (size_t)row * 1024 + c) = o; }
.LBB0_1787:
	s_andn2_b64 vcc, exec, s[24:25]
	s_cbranch_vccnz .LBB0_1789
	v_lshlrev_b64 v[72:73], 2, v[136:137]
	v_mul_f32_e32 v76, 0xbfb8aa3b, v64
	v_mul_f32_e32 v77, 0xbfb8aa3b, v65
	v_mul_f32_e32 v78, 0xbfb8aa3b, v66
	v_mul_f32_e32 v79, 0xbfb8aa3b, v67
	v_exp_f32_e32 v76, v76
	v_exp_f32_e32 v77, v77
	v_exp_f32_e32 v78, v78
	v_exp_f32_e32 v79, v79
	v_add_f32_e32 v76, 1.0, v76
	v_add_f32_e32 v77, 1.0, v77
	v_add_f32_e32 v78, 1.0, v78
	v_add_f32_e32 v79, 1.0, v79
	v_rcp_f32_e32 v76, v76
	v_rcp_f32_e32 v77, v77
	v_rcp_f32_e32 v78, v78
	v_rcp_f32_e32 v79, v79
	v_lshl_add_u64 v[74:75], s[20:21], 0, v[80:81]
	v_lshl_add_u64 v[72:73], v[74:75], 0, v[72:73]
	v_sub_f32_e32 v81, 1.0, v251
	v_sub_f32_e32 v80, 1.0, v250
	v_sub_f32_e32 v83, 1.0, v253
	v_sub_f32_e32 v82, 1.0, v252
	v_pk_fma_f32 v[70:71], v[78:79], v[82:83], v[252:253]
	v_pk_fma_f32 v[68:69], v[76:77], v[80:81], v[250:251]
	global_store_dwordx4 v[72:73], v[68:71], off offset:-1472

; __device__ __forceinline__ float sigmoidf_(float v) { return __builtin_amdgcn_rcpf(1.0f + __expf(-v)); }
; __device__ __forceinline__ float siluf_(float v) { return v * sigmoidf_(v); }
; __device__ __forceinline__ void store_bf16x4(bf16_t* p, f32x4 v) { u32x2 w; w.x = cvt_pk_bf16(v[0], v[1]); w.y = cvt_pk_bf16(v[2], v[3]); *(u32x2*)p = w; }
;   __device__ __forceinline__ void operator()(const f32x4 (&acc)[2][2][4][2], const pg8::Unit& u, int wr, int wc, int fr, int fq) const {
;     ...
;       if (pn < 2) { f32x4 o; for (int j = 0; j < 4; ++j) o[j] = siluf_(v[j]); store_bf16x4(QH + (size_t)row * 512 + col, o); }
;       else if (pn < 6) { const int c = col - 512; const f32x4 lb = *(const f32x4*)(LBj + c); f32x4 o; for (int j = 0; j < 4; ++j) o[j] = lb[j] + (1.f - lb[j]) * sigmoidf_(v[j]); *(f32x4*)(F + (size_t)row * 1024 + c) = o; }
.LBB0_1809:
	s_andn2_b64 vcc, exec, s[24:25]
	s_cbranch_vccnz .LBB0_1811
	v_lshlrev_b64 v[74:75], 2, v[136:137]
	v_mul_f32_e32 v76, 0xbfb8aa3b, v60
	v_mul_f32_e32 v77, 0xbfb8aa3b, v61
	v_exp_f32_e32 v76, v76
	v_exp_f32_e32 v77, v77
	v_mul_f32_e32 v78, 0xbfb8aa3b, v62
	v_mul_f32_e32 v79, 0xbfb8aa3b, v63
	v_exp_f32_e32 v78, v78
	v_exp_f32_e32 v79, v79
	v_add_f32_e32 v76, 1.0, v76
	v_add_f32_e32 v77, 1.0, v77
	v_rcp_f32_e32 v76, v76
	v_rcp_f32_e32 v77, v77
	v_add_f32_e32 v78, 1.0, v78
	v_add_f32_e32 v79, 1.0, v79
	v_rcp_f32_e32 v78, v78
	v_rcp_f32_e32 v79, v79
	v_sub_f32_e32 v81, 1.0, v239
	v_sub_f32_e32 v80, 1.0, v238
	v_sub_f32_e32 v83, 1.0, v241
	v_sub_f32_e32 v82, 1.0, v240
	v_pk_fma_f32 v[70:71], v[76:77], v[80:81], v[238:239]
	v_lshl_add_u64 v[76:77], s[20:21], 0, v[64:65]
	v_pk_fma_f32 v[72:73], v[78:79], v[82:83], v[240:241]
	v_lshl_add_u64 v[74:75], v[76:77], 0, v[74:75]
	global_store_dwordx4 v[74:75], v[70:73], off offset:-2048

; __device__ __forceinline__ float sigmoidf_(float v) { return __builtin_amdgcn_rcpf(1.0f + __expf(-v)); }
; __device__ __forceinline__ float siluf_(float v) { return v * sigmoidf_(v); }
; __device__ __forceinline__ void store_bf16x4(bf16_t* p, f32x4 v) { u32x2 w; w.x = cvt_pk_bf16(v[0], v[1]); w.y = cvt_pk_bf16(v[2], v[3]); *(u32x2*)p = w; }
;   __device__ __forceinline__ void operator()(const f32x4 (&acc)[2][2][4][2], const pg8::Unit& u, int wr, int wc, int fr, int fq) const {
;     const int pn = u.pn;
;     EPI_LOOP(
;       if (pn < 2) { f32x4 o; for (int j = 0; j < 4; ++j) o[j] = siluf_(v[j]); store_bf16x4(QH + (size_t)row * 512 + col, o); }
;       else if (pn < 6) { const int c = col - 512; const f32x4 lb = *(const f32x4*)(LBj + c); f32x4 o; for (int j = 0; j < 4; ++j) o[j] = lb[j] + (1.f - lb[j]) * sigmoidf_(v[j]); *(f32x4*)(F + (size_t)row * 1024 + c) = o; }
.LBB0_1823:
	s_andn2_b64 vcc, exec, s[24:25]
	s_cbranch_vccnz .LBB0_1825
	v_lshlrev_b64 v[72:73], 2, v[136:137]
	v_mul_f32_e32 v74, 0xbfb8aa3b, v56
	v_mul_f32_e32 v75, 0xbfb8aa3b, v57
	v_exp_f32_e32 v74, v74
	v_exp_f32_e32 v75, v75
	v_mul_f32_e32 v76, 0xbfb8aa3b, v58
	v_mul_f32_e32 v77, 0xbfb8aa3b, v59
	v_exp_f32_e32 v76, v76
	v_exp_f32_e32 v77, v77
	v_add_f32_e32 v74, 1.0, v74
	v_add_f32_e32 v75, 1.0, v75
	v_rcp_f32_e32 v74, v74
	v_rcp_f32_e32 v75, v75
	v_add_f32_e32 v76, 1.0, v76
	v_add_f32_e32 v77, 1.0, v77
	v_rcp_f32_e32 v76, v76
	v_rcp_f32_e32 v77, v77
	v_sub_f32_e32 v79, 1.0, v243
	v_sub_f32_e32 v78, 1.0, v242
	v_sub_f32_e32 v81, 1.0, v245
	v_sub_f32_e32 v80, 1.0, v244
	v_pk_fma_f32 v[60:61], v[74:75], v[78:79], v[242:243]
	v_lshl_add_u64 v[74:75], s[20:21], 0, v[64:65]
	v_pk_fma_f32 v[62:63], v[76:77], v[80:81], v[244:245]
	v_lshl_add_u64 v[72:73], v[74:75], 0, v[72:73]
	global_store_dwordx4 v[72:73], v[60:63], off offset:-1984

; __device__ __forceinline__ float sigmoidf_(float v) { return __builtin_amdgcn_rcpf(1.0f + __expf(-v)); }
; __device__ __forceinline__ float siluf_(float v) { return v * sigmoidf_(v); }
; __device__ __forceinline__ void store_bf16x4(bf16_t* p, f32x4 v) { u32x2 w; w.x = cvt_pk_bf16(v[0], v[1]); w.y = cvt_pk_bf16(v[2], v[3]); *(u32x2*)p = w; }
;   __device__ __forceinline__ void operator()(const f32x4 (&acc)[2][2][4][2], const pg8::Unit& u, int wr, int wc, int fr, int fq) const {
;     const int pn = u.pn;
;     EPI_LOOP(
;       if (pn < 2) { f32x4 o; for (int j = 0; j < 4; ++j) o[j] = siluf_(v[j]); store_bf16x4(QH + (size_t)row * 512 + col, o); }
;       else if (pn < 6) { const int c = col - 512; const f32x4 lb = *(const f32x4*)(LBj + c); f32x4 o; for (int j = 0; j < 4; ++j) o[j] = lb[j] + (1.f - lb[j]) * sigmoidf_(v[j]); *(f32x4*)(F + (size_t)row * 1024 + c) = o; }
.LBB0_1837:
	s_andn2_b64 vcc, exec, s[24:25]
	s_cbranch_vccnz .LBB0_1839
	v_lshlrev_b64 v[60:61], 2, v[136:137]
	v_mul_f32_e32 v62, 0xbfb8aa3b, v52
	v_mul_f32_e32 v63, 0xbfb8aa3b, v53
	v_exp_f32_e32 v62, v62
	v_exp_f32_e32 v63, v63
	v_mul_f32_e32 v72, 0xbfb8aa3b, v54
	v_mul_f32_e32 v73, 0xbfb8aa3b, v55
	v_exp_f32_e32 v72, v72
	v_exp_f32_e32 v73, v73
	v_add_f32_e32 v62, 1.0, v62
	v_add_f32_e32 v63, 1.0, v63
	v_rcp_f32_e32 v62, v62
	v_rcp_f32_e32 v63, v63
	v_add_f32_e32 v72, 1.0, v72
	v_add_f32_e32 v73, 1.0, v73
	v_rcp_f32_e32 v72, v72
	v_rcp_f32_e32 v73, v73
	v_sub_f32_e32 v75, 1.0, v247
	v_sub_f32_e32 v74, 1.0, v246
	v_sub_f32_e32 v77, 1.0, v249
	v_sub_f32_e32 v76, 1.0, v248
	v_pk_fma_f32 v[56:57], v[62:63], v[74:75], v[246:247]
	v_lshl_add_u64 v[62:63], s[20:21], 0, v[64:65]
	v_pk_fma_f32 v[58:59], v[72:73], v[76:77], v[248:249]
	v_lshl_add_u64 v[60:61], v[62:63], 0, v[60:61]
	global_store_dwordx4 v[60:61], v[56:59], off offset:-1536

; __device__ __forceinline__ float sigmoidf_(float v) { return __builtin_amdgcn_rcpf(1.0f + __expf(-v)); }
; __device__ __forceinline__ float siluf_(float v) { return v * sigmoidf_(v); }
; __device__ __forceinline__ void store_bf16x4(bf16_t* p, f32x4 v) { u32x2 w; w.x = cvt_pk_bf16(v[0], v[1]); w.y = cvt_pk_bf16(v[2], v[3]); *(u32x2*)p = w; }
;   __device__ __forceinline__ void operator()(const f32x4 (&acc)[2][2][4][2], const pg8::Unit& u, int wr, int wc, int fr, int fq) const {
;     const int pn = u.pn;
;     EPI_LOOP(
;       if (pn < 2) { f32x4 o; for (int j = 0; j < 4; ++j) o[j] = siluf_(v[j]); store_bf16x4(QH + (size_t)row * 512 + col, o); }
;       else if (pn < 6) { const int c = col - 512; const f32x4 lb = *(const f32x4*)(LBj + c); f32x4 o; for (int j = 0; j < 4; ++j) o[j] = lb[j] + (1.f - lb[j]) * sigmoidf_(v[j]); *(f32x4*)(F + (size_t)row * 1024 + c) = o; }
.LBB0_1851:
	s_andn2_b64 vcc, exec, s[24:25]
	s_cbranch_vccnz .LBB0_1853
	v_lshlrev_b64 v[56:57], 2, v[136:137]
	v_mul_f32_e32 v60, 0xbfb8aa3b, v48
	v_mul_f32_e32 v61, 0xbfb8aa3b, v49
	v_mul_f32_e32 v62, 0xbfb8aa3b, v50
	v_mul_f32_e32 v63, 0xbfb8aa3b, v51
	v_exp_f32_e32 v60, v60
	v_exp_f32_e32 v61, v61
	v_exp_f32_e32 v62, v62
	v_exp_f32_e32 v63, v63
	v_add_f32_e32 v60, 1.0, v60
	v_add_f32_e32 v61, 1.0, v61
	v_add_f32_e32 v62, 1.0, v62
	v_add_f32_e32 v63, 1.0, v63
	v_rcp_f32_e32 v60, v60
	v_rcp_f32_e32 v61, v61
	v_rcp_f32_e32 v62, v62
	v_rcp_f32_e32 v63, v63
	v_lshl_add_u64 v[58:59], s[20:21], 0, v[64:65]
	v_lshl_add_u64 v[56:57], v[58:59], 0, v[56:57]
	v_sub_f32_e32 v65, 1.0, v251
	v_sub_f32_e32 v64, 1.0, v250
	v_sub_f32_e32 v67, 1.0, v253
	v_sub_f32_e32 v66, 1.0, v252
	v_pk_fma_f32 v[54:55], v[62:63], v[66:67], v[252:253]
	v_pk_fma_f32 v[52:53], v[60:61], v[64:65], v[250:251]
	global_store_dwordx4 v[56:57], v[52:55], off offset:-1472

; __device__ __forceinline__ float sigmoidf_(float v) { return __builtin_amdgcn_rcpf(1.0f + __expf(-v)); }
; __device__ __forceinline__ float siluf_(float v) { return v * sigmoidf_(v); }
; __device__ __forceinline__ void store_bf16x4(bf16_t* p, f32x4 v) { u32x2 w; w.x = cvt_pk_bf16(v[0], v[1]); w.y = cvt_pk_bf16(v[2], v[3]); *(u32x2*)p = w; }
;   __device__ __forceinline__ void operator()(const f32x4 (&acc)[2][2][4][2], const pg8::Unit& u, int wr, int wc, int fr, int fq) const {
;     const int pn = u.pn;
;     EPI_LOOP(
;       if (pn < 2) { f32x4 o; for (int j = 0; j < 4; ++j) o[j] = siluf_(v[j]); store_bf16x4(QH + (size_t)row * 512 + col, o); }
;       else if (pn < 6) { const int c = col - 512; const f32x4 lb = *(const f32x4*)(LBj + c); f32x4 o; for (int j = 0; j < 4; ++j) o[j] = lb[j] + (1.f - lb[j]) * sigmoidf_(v[j]); *(f32x4*)(F + (size_t)row * 1024 + c) = o; }
.LBB0_1873:
	s_andn2_b64 vcc, exec, s[24:25]
	s_cbranch_vccnz .LBB0_1875
	v_lshlrev_b64 v[58:59], 2, v[136:137]
	v_mul_f32_e32 v60, 0xbfb8aa3b, v44
	v_mul_f32_e32 v61, 0xbfb8aa3b, v45
	v_exp_f32_e32 v60, v60
	v_exp_f32_e32 v61, v61
	v_mul_f32_e32 v62, 0xbfb8aa3b, v46
	v_mul_f32_e32 v63, 0xbfb8aa3b, v47
	v_exp_f32_e32 v62, v62
	v_exp_f32_e32 v63, v63
	v_add_f32_e32 v60, 1.0, v60
	v_add_f32_e32 v61, 1.0, v61
	v_rcp_f32_e32 v60, v60
	v_rcp_f32_e32 v61, v61
	v_add_f32_e32 v62, 1.0, v62
	v_add_f32_e32 v63, 1.0, v63
	v_rcp_f32_e32 v62, v62
	v_rcp_f32_e32 v63, v63
	v_sub_f32_e32 v65, 1.0, v239
	v_sub_f32_e32 v64, 1.0, v238
	v_sub_f32_e32 v67, 1.0, v241
	v_sub_f32_e32 v66, 1.0, v240
	v_pk_fma_f32 v[54:55], v[60:61], v[64:65], v[238:239]
	v_lshl_add_u64 v[60:61], s[20:21], 0, v[48:49]
	v_pk_fma_f32 v[56:57], v[62:63], v[66:67], v[240:241]
	v_lshl_add_u64 v[58:59], v[60:61], 0, v[58:59]
	global_store_dwordx4 v[58:59], v[54:57], off offset:-2048

; __device__ __forceinline__ float sigmoidf_(float v) { return __builtin_amdgcn_rcpf(1.0f + __expf(-v)); }
; __device__ __forceinline__ float siluf_(float v) { return v * sigmoidf_(v); }
; __device__ __forceinline__ void store_bf16x4(bf16_t* p, f32x4 v) { u32x2 w; w.x = cvt_pk_bf16(v[0], v[1]); w.y = cvt_pk_bf16(v[2], v[3]); *(u32x2*)p = w; }
;   __device__ __forceinline__ void operator()(const f32x4 (&acc)[2][2][4][2], const pg8::Unit& u, int wr, int wc, int fr, int fq) const {
;     const int pn = u.pn;
;     EPI_LOOP(
;       if (pn < 2) { f32x4 o; for (int j = 0; j < 4; ++j) o[j] = siluf_(v[j]); store_bf16x4(QH + (size_t)row * 512 + col, o); }
;       else if (pn < 6) { const int c = col - 512; const f32x4 lb = *(const f32x4*)(LBj + c); f32x4 o; for (int j = 0; j < 4; ++j) o[j] = lb[j] + (1.f - lb[j]) * sigmoidf_(v[j]); *(f32x4*)(F + (size_t)row * 1024 + c) = o; }
.LBB0_1887:
	s_andn2_b64 vcc, exec, s[24:25]
	s_cbranch_vccnz .LBB0_1889
	v_lshlrev_b64 v[56:57], 2, v[136:137]
	v_mul_f32_e32 v58, 0xbfb8aa3b, v40
	v_mul_f32_e32 v59, 0xbfb8aa3b, v41
	v_exp_f32_e32 v58, v58
	v_exp_f32_e32 v59, v59
	v_mul_f32_e32 v60, 0xbfb8aa3b, v42
	v_mul_f32_e32 v61, 0xbfb8aa3b, v43
	v_exp_f32_e32 v60, v60
	v_exp_f32_e32 v61, v61
	v_add_f32_e32 v58, 1.0, v58
	v_add_f32_e32 v59, 1.0, v59
	v_rcp_f32_e32 v58, v58
	v_rcp_f32_e32 v59, v59
	v_add_f32_e32 v60, 1.0, v60
	v_add_f32_e32 v61, 1.0, v61
	v_rcp_f32_e32 v60, v60
	v_rcp_f32_e32 v61, v61
	v_sub_f32_e32 v63, 1.0, v243
	v_sub_f32_e32 v62, 1.0, v242
	v_sub_f32_e32 v65, 1.0, v245
	v_sub_f32_e32 v64, 1.0, v244
	v_pk_fma_f32 v[44:45], v[58:59], v[62:63], v[242:243]
	v_lshl_add_u64 v[58:59], s[20:21], 0, v[48:49]
	v_pk_fma_f32 v[46:47], v[60:61], v[64:65], v[244:245]
	v_lshl_add_u64 v[56:57], v[58:59], 0, v[56:57]
	global_store_dwordx4 v[56:57], v[44:47], off offset:-1984

; __device__ __forceinline__ float sigmoidf_(float v) { return __builtin_amdgcn_rcpf(1.0f + __expf(-v)); }
; __device__ __forceinline__ float siluf_(float v) { return v * sigmoidf_(v); }
; __device__ __forceinline__ void store_bf16x4(bf16_t* p, f32x4 v) { u32x2 w; w.x = cvt_pk_bf16(v[0], v[1]); w.y = cvt_pk_bf16(v[2], v[3]); *(u32x2*)p = w; }
;   __device__ __forceinline__ void operator()(const f32x4 (&acc)[2][2][4][2], const pg8::Unit& u, int wr, int wc, int fr, int fq) const {
;     const int pn = u.pn;
;     EPI_LOOP(
;       if (pn < 2) { f32x4 o; for (int j = 0; j < 4; ++j) o[j] = siluf_(v[j]); store_bf16x4(QH + (size_t)row * 512 + col, o); }
;       else if (pn < 6) { const int c = col - 512; const f32x4 lb = *(const f32x4*)(LBj + c); f32x4 o; for (int j = 0; j < 4; ++j) o[j] = lb[j] + (1.f - lb[j]) * sigmoidf_(v[j]); *(f32x4*)(F + (size_t)row * 1024 + c) = o; }
.LBB0_1901:
	s_andn2_b64 vcc, exec, s[24:25]
	s_cbranch_vccnz .LBB0_1903
	v_lshlrev_b64 v[44:45], 2, v[136:137]
	v_mul_f32_e32 v46, 0xbfb8aa3b, v36
	v_mul_f32_e32 v47, 0xbfb8aa3b, v37
	v_exp_f32_e32 v46, v46
	v_exp_f32_e32 v47, v47
	v_mul_f32_e32 v56, 0xbfb8aa3b, v38
	v_mul_f32_e32 v57, 0xbfb8aa3b, v39
	v_exp_f32_e32 v56, v56
	v_exp_f32_e32 v57, v57
	v_add_f32_e32 v46, 1.0, v46
	v_add_f32_e32 v47, 1.0, v47
	v_rcp_f32_e32 v46, v46
	v_rcp_f32_e32 v47, v47
	v_add_f32_e32 v56, 1.0, v56
	v_add_f32_e32 v57, 1.0, v57
	v_rcp_f32_e32 v56, v56
	v_rcp_f32_e32 v57, v57
	v_sub_f32_e32 v59, 1.0, v247
	v_sub_f32_e32 v58, 1.0, v246
	v_sub_f32_e32 v61, 1.0, v249
	v_sub_f32_e32 v60, 1.0, v248
	v_pk_fma_f32 v[40:41], v[46:47], v[58:59], v[246:247]
	v_lshl_add_u64 v[46:47], s[20:21], 0, v[48:49]
	v_pk_fma_f32 v[42:43], v[56:57], v[60:61], v[248:249]
	v_lshl_add_u64 v[44:45], v[46:47], 0, v[44:45]
	global_store_dwordx4 v[44:45], v[40:43], off offset:-1536

; __device__ __forceinline__ float sigmoidf_(float v) { return __builtin_amdgcn_rcpf(1.0f + __expf(-v)); }
; __device__ __forceinline__ float siluf_(float v) { return v * sigmoidf_(v); }
; __device__ __forceinline__ void store_bf16x4(bf16_t* p, f32x4 v) { u32x2 w; w.x = cvt_pk_bf16(v[0], v[1]); w.y = cvt_pk_bf16(v[2], v[3]); *(u32x2*)p = w; }
;   __device__ __forceinline__ void operator()(const f32x4 (&acc)[2][2][4][2], const pg8::Unit& u, int wr, int wc, int fr, int fq) const {
;     const int pn = u.pn;
;     EPI_LOOP(
;       if (pn < 2) { f32x4 o; for (int j = 0; j < 4; ++j) o[j] = siluf_(v[j]); store_bf16x4(QH + (size_t)row * 512 + col, o); }
;       else if (pn < 6) { const int c = col - 512; const f32x4 lb = *(const f32x4*)(LBj + c); f32x4 o; for (int j = 0; j < 4; ++j) o[j] = lb[j] + (1.f - lb[j]) * sigmoidf_(v[j]); *(f32x4*)(F + (size_t)row * 1024 + c) = o; }
.LBB0_1915:
	s_andn2_b64 vcc, exec, s[24:25]
	s_cbranch_vccnz .LBB0_1917
	v_lshlrev_b64 v[40:41], 2, v[136:137]
	v_mul_f32_e32 v44, 0xbfb8aa3b, v32
	v_mul_f32_e32 v45, 0xbfb8aa3b, v33
	v_mul_f32_e32 v46, 0xbfb8aa3b, v34
	v_mul_f32_e32 v47, 0xbfb8aa3b, v35
	v_exp_f32_e32 v44, v44
	v_exp_f32_e32 v45, v45
	v_exp_f32_e32 v46, v46
	v_exp_f32_e32 v47, v47
	v_add_f32_e32 v44, 1.0, v44
	v_add_f32_e32 v45, 1.0, v45
	v_add_f32_e32 v46, 1.0, v46
	v_add_f32_e32 v47, 1.0, v47
	v_rcp_f32_e32 v44, v44
	v_rcp_f32_e32 v45, v45
	v_rcp_f32_e32 v46, v46
	v_rcp_f32_e32 v47, v47
	v_lshl_add_u64 v[42:43], s[20:21], 0, v[48:49]
	v_lshl_add_u64 v[40:41], v[42:43], 0, v[40:41]
	v_sub_f32_e32 v49, 1.0, v251
	v_sub_f32_e32 v48, 1.0, v250
	v_sub_f32_e32 v51, 1.0, v253
	v_sub_f32_e32 v50, 1.0, v252
	v_pk_fma_f32 v[38:39], v[46:47], v[50:51], v[252:253]
	v_pk_fma_f32 v[36:37], v[44:45], v[48:49], v[250:251]
	global_store_dwordx4 v[40:41], v[36:39], off offset:-1472

; __device__ __forceinline__ float sigmoidf_(float v) { return __builtin_amdgcn_rcpf(1.0f + __expf(-v)); }
; __device__ __forceinline__ float siluf_(float v) { return v * sigmoidf_(v); }
; __device__ __forceinline__ void store_bf16x4(bf16_t* p, f32x4 v) { u32x2 w; w.x = cvt_pk_bf16(v[0], v[1]); w.y = cvt_pk_bf16(v[2], v[3]); *(u32x2*)p = w; }
;   __device__ __forceinline__ void operator()(const f32x4 (&acc)[2][2][4][2], const pg8::Unit& u, int wr, int wc, int fr, int fq) const {
;     const int pn = u.pn;
;     EPI_LOOP(
;       if (pn < 2) { f32x4 o; for (int j = 0; j < 4; ++j) o[j] = siluf_(v[j]); store_bf16x4(QH + (size_t)row * 512 + col, o); }
;       else if (pn < 6) { const int c = col - 512; const f32x4 lb = *(const f32x4*)(LBj + c); f32x4 o; for (int j = 0; j < 4; ++j) o[j] = lb[j] + (1.f - lb[j]) * sigmoidf_(v[j]); *(f32x4*)(F + (size_t)row * 1024 + c) = o; }
.LBB0_1937:
	s_andn2_b64 vcc, exec, s[24:25]
	s_cbranch_vccnz .LBB0_1939
	v_lshlrev_b64 v[42:43], 2, v[136:137]
	v_mul_f32_e32 v44, 0xbfb8aa3b, v28
	v_mul_f32_e32 v45, 0xbfb8aa3b, v29
	v_exp_f32_e32 v44, v44
	v_exp_f32_e32 v45, v45
	v_mul_f32_e32 v46, 0xbfb8aa3b, v30
	v_mul_f32_e32 v47, 0xbfb8aa3b, v31
	v_exp_f32_e32 v46, v46
	v_exp_f32_e32 v47, v47
	v_add_f32_e32 v44, 1.0, v44
	v_add_f32_e32 v45, 1.0, v45
	v_rcp_f32_e32 v44, v44
	v_rcp_f32_e32 v45, v45
	v_add_f32_e32 v46, 1.0, v46
	v_add_f32_e32 v47, 1.0, v47
	v_rcp_f32_e32 v46, v46
	v_rcp_f32_e32 v47, v47
	v_sub_f32_e32 v49, 1.0, v239
	v_sub_f32_e32 v48, 1.0, v238
	v_sub_f32_e32 v51, 1.0, v241
	v_sub_f32_e32 v50, 1.0, v240
	v_pk_fma_f32 v[38:39], v[44:45], v[48:49], v[238:239]
	v_lshl_add_u64 v[44:45], s[20:21], 0, v[32:33]
	v_pk_fma_f32 v[40:41], v[46:47], v[50:51], v[240:241]
	v_lshl_add_u64 v[42:43], v[44:45], 0, v[42:43]
	global_store_dwordx4 v[42:43], v[38:41], off offset:-2048

; __device__ __forceinline__ float sigmoidf_(float v) { return __builtin_amdgcn_rcpf(1.0f + __expf(-v)); }
; __device__ __forceinline__ float siluf_(float v) { return v * sigmoidf_(v); }
; __device__ __forceinline__ void store_bf16x4(bf16_t* p, f32x4 v) { u32x2 w; w.x = cvt_pk_bf16(v[0], v[1]); w.y = cvt_pk_bf16(v[2], v[3]); *(u32x2*)p = w; }
;   __device__ __forceinline__ void operator()(const f32x4 (&acc)[2][2][4][2], const pg8::Unit& u, int wr, int wc, int fr, int fq) const {
;     const int pn = u.pn;
;     EPI_LOOP(
;       if (pn < 2) { f32x4 o; for (int j = 0; j < 4; ++j) o[j] = siluf_(v[j]); store_bf16x4(QH + (size_t)row * 512 + col, o); }
;       else if (pn < 6) { const int c = col - 512; const f32x4 lb = *(const f32x4*)(LBj + c); f32x4 o; for (int j = 0; j < 4; ++j) o[j] = lb[j] + (1.f - lb[j]) * sigmoidf_(v[j]); *(f32x4*)(F + (size_t)row * 1024 + c) = o; }
.LBB0_1951:
	s_andn2_b64 vcc, exec, s[24:25]
	s_cbranch_vccnz .LBB0_1953
	v_lshlrev_b64 v[40:41], 2, v[136:137]
	v_mul_f32_e32 v42, 0xbfb8aa3b, v24
	v_mul_f32_e32 v43, 0xbfb8aa3b, v25
	v_exp_f32_e32 v42, v42
	v_exp_f32_e32 v43, v43
	v_mul_f32_e32 v44, 0xbfb8aa3b, v26
	v_mul_f32_e32 v45, 0xbfb8aa3b, v27
	v_exp_f32_e32 v44, v44
	v_exp_f32_e32 v45, v45
	v_add_f32_e32 v42, 1.0, v42
	v_add_f32_e32 v43, 1.0, v43
	v_rcp_f32_e32 v42, v42
	v_rcp_f32_e32 v43, v43
	v_add_f32_e32 v44, 1.0, v44
	v_add_f32_e32 v45, 1.0, v45
	v_rcp_f32_e32 v44, v44
	v_rcp_f32_e32 v45, v45
	v_sub_f32_e32 v47, 1.0, v243
	v_sub_f32_e32 v46, 1.0, v242
	v_sub_f32_e32 v49, 1.0, v245
	v_sub_f32_e32 v48, 1.0, v244
	v_pk_fma_f32 v[28:29], v[42:43], v[46:47], v[242:243]
	v_lshl_add_u64 v[42:43], s[20:21], 0, v[32:33]
	v_pk_fma_f32 v[30:31], v[44:45], v[48:49], v[244:245]
	v_lshl_add_u64 v[40:41], v[42:43], 0, v[40:41]
	global_store_dwordx4 v[40:41], v[28:31], off offset:-1984

; __device__ __forceinline__ float sigmoidf_(float v) { return __builtin_amdgcn_rcpf(1.0f + __expf(-v)); }
; __device__ __forceinline__ float siluf_(float v) { return v * sigmoidf_(v); }
; __device__ __forceinline__ void store_bf16x4(bf16_t* p, f32x4 v) { u32x2 w; w.x = cvt_pk_bf16(v[0], v[1]); w.y = cvt_pk_bf16(v[2], v[3]); *(u32x2*)p = w; }
;   __device__ __forceinline__ void operator()(const f32x4 (&acc)[2][2][4][2], const pg8::Unit& u, int wr, int wc, int fr, int fq) const {
;     const int pn = u.pn;
;     EPI_LOOP(
;       if (pn < 2) { f32x4 o; for (int j = 0; j < 4; ++j) o[j] = siluf_(v[j]); store_bf16x4(QH + (size_t)row * 512 + col, o); }
;       else if (pn < 6) { const int c = col - 512; const f32x4 lb = *(const f32x4*)(LBj + c); f32x4 o; for (int j = 0; j < 4; ++j) o[j] = lb[j] + (1.f - lb[j]) * sigmoidf_(v[j]); *(f32x4*)(F + (size_t)row * 1024 + c) = o; }
.LBB0_1965:
	s_andn2_b64 vcc, exec, s[24:25]
	s_cbranch_vccnz .LBB0_1967
	v_lshlrev_b64 v[28:29], 2, v[136:137]
	v_mul_f32_e32 v30, 0xbfb8aa3b, v20
	v_mul_f32_e32 v31, 0xbfb8aa3b, v21
	v_exp_f32_e32 v30, v30
	v_exp_f32_e32 v31, v31
	v_mul_f32_e32 v40, 0xbfb8aa3b, v22
	v_mul_f32_e32 v41, 0xbfb8aa3b, v23
	v_exp_f32_e32 v40, v40
	v_exp_f32_e32 v41, v41
	v_add_f32_e32 v30, 1.0, v30
	v_add_f32_e32 v31, 1.0, v31
	v_rcp_f32_e32 v30, v30
	v_rcp_f32_e32 v31, v31
	v_add_f32_e32 v40, 1.0, v40
	v_add_f32_e32 v41, 1.0, v41
	v_rcp_f32_e32 v40, v40
	v_rcp_f32_e32 v41, v41
	v_sub_f32_e32 v43, 1.0, v247
	v_sub_f32_e32 v42, 1.0, v246
	v_sub_f32_e32 v45, 1.0, v249
	v_sub_f32_e32 v44, 1.0, v248
	v_pk_fma_f32 v[24:25], v[30:31], v[42:43], v[246:247]
	v_lshl_add_u64 v[30:31], s[20:21], 0, v[32:33]
	v_pk_fma_f32 v[26:27], v[40:41], v[44:45], v[248:249]
	v_lshl_add_u64 v[28:29], v[30:31], 0, v[28:29]
	global_store_dwordx4 v[28:29], v[24:27], off offset:-1536

; __device__ __forceinline__ float sigmoidf_(float v) { return __builtin_amdgcn_rcpf(1.0f + __expf(-v)); }
; __device__ __forceinline__ float siluf_(float v) { return v * sigmoidf_(v); }
; __device__ __forceinline__ void store_bf16x4(bf16_t* p, f32x4 v) { u32x2 w; w.x = cvt_pk_bf16(v[0], v[1]); w.y = cvt_pk_bf16(v[2], v[3]); *(u32x2*)p = w; }
;   __device__ __forceinline__ void operator()(const f32x4 (&acc)[2][2][4][2], const pg8::Unit& u, int wr, int wc, int fr, int fq) const {
;     const int pn = u.pn;
;     EPI_LOOP(
;       if (pn < 2) { f32x4 o; for (int j = 0; j < 4; ++j) o[j] = siluf_(v[j]); store_bf16x4(QH + (size_t)row * 512 + col, o); }
;       else if (pn < 6) { const int c = col - 512; const f32x4 lb = *(const f32x4*)(LBj + c); f32x4 o; for (int j = 0; j < 4; ++j) o[j] = lb[j] + (1.f - lb[j]) * sigmoidf_(v[j]); *(f32x4*)(F + (size_t)row * 1024 + c) = o; }
.LBB0_1979:
	s_andn2_b64 vcc, exec, s[24:25]
	s_cbranch_vccnz .LBB0_1981
	v_lshlrev_b64 v[24:25], 2, v[136:137]
	v_mul_f32_e32 v28, 0xbfb8aa3b, v16
	v_mul_f32_e32 v29, 0xbfb8aa3b, v17
	v_mul_f32_e32 v30, 0xbfb8aa3b, v18
	v_mul_f32_e32 v31, 0xbfb8aa3b, v19
	v_exp_f32_e32 v28, v28
	v_exp_f32_e32 v29, v29
	v_exp_f32_e32 v30, v30
	v_exp_f32_e32 v31, v31
	v_add_f32_e32 v28, 1.0, v28
	v_add_f32_e32 v29, 1.0, v29
	v_add_f32_e32 v30, 1.0, v30
	v_add_f32_e32 v31, 1.0, v31
	v_rcp_f32_e32 v28, v28
	v_rcp_f32_e32 v29, v29
	v_rcp_f32_e32 v30, v30
	v_rcp_f32_e32 v31, v31
	v_lshl_add_u64 v[26:27], s[20:21], 0, v[32:33]
	v_lshl_add_u64 v[24:25], v[26:27], 0, v[24:25]
	v_sub_f32_e32 v33, 1.0, v251
	v_sub_f32_e32 v32, 1.0, v250
	v_sub_f32_e32 v35, 1.0, v253
	v_sub_f32_e32 v34, 1.0, v252
	v_pk_fma_f32 v[22:23], v[30:31], v[34:35], v[252:253]
	v_pk_fma_f32 v[20:21], v[28:29], v[32:33], v[250:251]
	global_store_dwordx4 v[24:25], v[20:23], off offset:-1472

; __device__ __forceinline__ float sigmoidf_(float v) { return __builtin_amdgcn_rcpf(1.0f + __expf(-v)); }
; __device__ __forceinline__ float siluf_(float v) { return v * sigmoidf_(v); }
; __device__ __forceinline__ void store_bf16x4(bf16_t* p, f32x4 v) { u32x2 w; w.x = cvt_pk_bf16(v[0], v[1]); w.y = cvt_pk_bf16(v[2], v[3]); *(u32x2*)p = w; }
;   __device__ __forceinline__ void operator()(const f32x4 (&acc)[2][2][4][2], const pg8::Unit& u, int wr, int wc, int fr, int fq) const {
;     const int pn = u.pn;
;     EPI_LOOP(
;       if (pn < 2) { f32x4 o; for (int j = 0; j < 4; ++j) o[j] = siluf_(v[j]); store_bf16x4(QH + (size_t)row * 512 + col, o); }
;       else if (pn < 6) { const int c = col - 512; const f32x4 lb = *(const f32x4*)(LBj + c); f32x4 o; for (int j = 0; j < 4; ++j) o[j] = lb[j] + (1.f - lb[j]) * sigmoidf_(v[j]); *(f32x4*)(F + (size_t)row * 1024 + c) = o; }
.LBB0_2001:
	s_andn2_b64 vcc, exec, s[24:25]
	s_cbranch_vccnz .LBB0_2003
	v_lshlrev_b64 v[26:27], 2, v[136:137]
	v_mul_f32_e32 v28, 0xbfb8aa3b, v12
	v_mul_f32_e32 v29, 0xbfb8aa3b, v13
	v_exp_f32_e32 v28, v28
	v_exp_f32_e32 v29, v29
	v_mul_f32_e32 v30, 0xbfb8aa3b, v14
	v_mul_f32_e32 v31, 0xbfb8aa3b, v15
	v_exp_f32_e32 v30, v30
	v_exp_f32_e32 v31, v31
	v_add_f32_e32 v28, 1.0, v28
	v_add_f32_e32 v29, 1.0, v29
	v_rcp_f32_e32 v28, v28
	v_rcp_f32_e32 v29, v29
	v_add_f32_e32 v30, 1.0, v30
	v_add_f32_e32 v31, 1.0, v31
	v_rcp_f32_e32 v30, v30
	v_rcp_f32_e32 v31, v31
	v_sub_f32_e32 v33, 1.0, v239
	v_sub_f32_e32 v32, 1.0, v238
	v_sub_f32_e32 v35, 1.0, v241
	v_sub_f32_e32 v34, 1.0, v240
	v_pk_fma_f32 v[22:23], v[28:29], v[32:33], v[238:239]
	v_lshl_add_u64 v[28:29], s[20:21], 0, v[16:17]
	v_pk_fma_f32 v[24:25], v[30:31], v[34:35], v[240:241]
	v_lshl_add_u64 v[26:27], v[28:29], 0, v[26:27]
	global_store_dwordx4 v[26:27], v[22:25], off offset:-2048

; __device__ __forceinline__ float sigmoidf_(float v) { return __builtin_amdgcn_rcpf(1.0f + __expf(-v)); }
; __device__ __forceinline__ float siluf_(float v) { return v * sigmoidf_(v); }
; __device__ __forceinline__ void store_bf16x4(bf16_t* p, f32x4 v) { u32x2 w; w.x = cvt_pk_bf16(v[0], v[1]); w.y = cvt_pk_bf16(v[2], v[3]); *(u32x2*)p = w; }
;   __device__ __forceinline__ void operator()(const f32x4 (&acc)[2][2][4][2], const pg8::Unit& u, int wr, int wc, int fr, int fq) const {
;     const int pn = u.pn;
;     EPI_LOOP(
;       if (pn < 2) { f32x4 o; for (int j = 0; j < 4; ++j) o[j] = siluf_(v[j]); store_bf16x4(QH + (size_t)row * 512 + col, o); }
;       else if (pn < 6) { const int c = col - 512; const f32x4 lb = *(const f32x4*)(LBj + c); f32x4 o; for (int j = 0; j < 4; ++j) o[j] = lb[j] + (1.f - lb[j]) * sigmoidf_(v[j]); *(f32x4*)(F + (size_t)row * 1024 + c) = o; }
.LBB0_2015:
	s_andn2_b64 vcc, exec, s[24:25]
	s_cbranch_vccnz .LBB0_2017
	v_lshlrev_b64 v[24:25], 2, v[136:137]
	v_mul_f32_e32 v26, 0xbfb8aa3b, v8
	v_mul_f32_e32 v27, 0xbfb8aa3b, v9
	v_exp_f32_e32 v26, v26
	v_exp_f32_e32 v27, v27
	v_mul_f32_e32 v28, 0xbfb8aa3b, v10
	v_mul_f32_e32 v29, 0xbfb8aa3b, v11
	v_exp_f32_e32 v28, v28
	v_exp_f32_e32 v29, v29
	v_add_f32_e32 v26, 1.0, v26
	v_add_f32_e32 v27, 1.0, v27
	v_rcp_f32_e32 v26, v26
	v_rcp_f32_e32 v27, v27
	v_add_f32_e32 v28, 1.0, v28
	v_add_f32_e32 v29, 1.0, v29
	v_rcp_f32_e32 v28, v28
	v_rcp_f32_e32 v29, v29
	v_sub_f32_e32 v31, 1.0, v243
	v_sub_f32_e32 v30, 1.0, v242
	v_sub_f32_e32 v33, 1.0, v245
	v_sub_f32_e32 v32, 1.0, v244
	v_pk_fma_f32 v[12:13], v[26:27], v[30:31], v[242:243]
	v_lshl_add_u64 v[26:27], s[20:21], 0, v[16:17]
	v_pk_fma_f32 v[14:15], v[28:29], v[32:33], v[244:245]
	v_lshl_add_u64 v[24:25], v[26:27], 0, v[24:25]
	global_store_dwordx4 v[24:25], v[12:15], off offset:-1984

; __device__ __forceinline__ float sigmoidf_(float v) { return __builtin_amdgcn_rcpf(1.0f + __expf(-v)); }
; __device__ __forceinline__ float siluf_(float v) { return v * sigmoidf_(v); }
; __device__ __forceinline__ void store_bf16x4(bf16_t* p, f32x4 v) { u32x2 w; w.x = cvt_pk_bf16(v[0], v[1]); w.y = cvt_pk_bf16(v[2], v[3]); *(u32x2*)p = w; }
;   __device__ __forceinline__ void operator()(const f32x4 (&acc)[2][2][4][2], const pg8::Unit& u, int wr, int wc, int fr, int fq) const {
;     const int pn = u.pn;
;     EPI_LOOP(
;       if (pn < 2) { f32x4 o; for (int j = 0; j < 4; ++j) o[j] = siluf_(v[j]); store_bf16x4(QH + (size_t)row * 512 + col, o); }
;       else if (pn < 6) { const int c = col - 512; const f32x4 lb = *(const f32x4*)(LBj + c); f32x4 o; for (int j = 0; j < 4; ++j) o[j] = lb[j] + (1.f - lb[j]) * sigmoidf_(v[j]); *(f32x4*)(F + (size_t)row * 1024 + c) = o; }
.LBB0_2029:
	s_andn2_b64 vcc, exec, s[24:25]
	s_cbranch_vccnz .LBB0_2031
	v_lshlrev_b64 v[12:13], 2, v[136:137]
	v_mul_f32_e32 v14, 0xbfb8aa3b, v4
	v_mul_f32_e32 v15, 0xbfb8aa3b, v5
	v_exp_f32_e32 v14, v14
	v_exp_f32_e32 v15, v15
	v_mul_f32_e32 v24, 0xbfb8aa3b, v6
	v_mul_f32_e32 v25, 0xbfb8aa3b, v7
	v_exp_f32_e32 v24, v24
	v_exp_f32_e32 v25, v25
	v_add_f32_e32 v14, 1.0, v14
	v_add_f32_e32 v15, 1.0, v15
	v_rcp_f32_e32 v14, v14
	v_rcp_f32_e32 v15, v15
	v_add_f32_e32 v24, 1.0, v24
	v_add_f32_e32 v25, 1.0, v25
	v_rcp_f32_e32 v24, v24
	v_rcp_f32_e32 v25, v25
	v_sub_f32_e32 v27, 1.0, v247
	v_sub_f32_e32 v26, 1.0, v246
	v_sub_f32_e32 v29, 1.0, v249
	v_sub_f32_e32 v28, 1.0, v248
	v_pk_fma_f32 v[8:9], v[14:15], v[26:27], v[246:247]
	v_lshl_add_u64 v[14:15], s[20:21], 0, v[16:17]
	v_pk_fma_f32 v[10:11], v[24:25], v[28:29], v[248:249]
	v_lshl_add_u64 v[12:13], v[14:15], 0, v[12:13]
	global_store_dwordx4 v[12:13], v[8:11], off offset:-1536

; __device__ __forceinline__ float sigmoidf_(float v) { return __builtin_amdgcn_rcpf(1.0f + __expf(-v)); }
; __device__ __forceinline__ float siluf_(float v) { return v * sigmoidf_(v); }
; __device__ __forceinline__ void store_bf16x4(bf16_t* p, f32x4 v) { u32x2 w; w.x = cvt_pk_bf16(v[0], v[1]); w.y = cvt_pk_bf16(v[2], v[3]); *(u32x2*)p = w; }
;   __device__ __forceinline__ void operator()(const f32x4 (&acc)[2][2][4][2], const pg8::Unit& u, int wr, int wc, int fr, int fq) const {
;     const int pn = u.pn;
;     EPI_LOOP(
;       if (pn < 2) { f32x4 o; for (int j = 0; j < 4; ++j) o[j] = siluf_(v[j]); store_bf16x4(QH + (size_t)row * 512 + col, o); }
;       else if (pn < 6) { const int c = col - 512; const f32x4 lb = *(const f32x4*)(LBj + c); f32x4 o; for (int j = 0; j < 4; ++j) o[j] = lb[j] + (1.f - lb[j]) * sigmoidf_(v[j]); *(f32x4*)(F + (size_t)row * 1024 + c) = o; }
.LBB0_2043:
	s_andn2_b64 vcc, exec, s[8:9]
	s_cbranch_vccnz .LBB0_2045
	v_lshlrev_b64 v[8:9], 2, v[136:137]
	v_mul_f32_e32 v12, 0xbfb8aa3b, v0
	v_mul_f32_e32 v13, 0xbfb8aa3b, v1
	v_mul_f32_e32 v14, 0xbfb8aa3b, v2
	v_mul_f32_e32 v15, 0xbfb8aa3b, v3
	v_exp_f32_e32 v12, v12
	v_exp_f32_e32 v13, v13
	v_exp_f32_e32 v14, v14
	v_exp_f32_e32 v15, v15
	v_add_f32_e32 v12, 1.0, v12
	v_add_f32_e32 v13, 1.0, v13
	v_add_f32_e32 v14, 1.0, v14
	v_add_f32_e32 v15, 1.0, v15
	v_rcp_f32_e32 v12, v12
	v_rcp_f32_e32 v13, v13
	v_rcp_f32_e32 v14, v14
	v_rcp_f32_e32 v15, v15
	v_lshl_add_u64 v[10:11], s[20:21], 0, v[16:17]
	v_lshl_add_u64 v[8:9], v[10:11], 0, v[8:9]
	v_sub_f32_e32 v17, 1.0, v251
	v_sub_f32_e32 v16, 1.0, v250
	v_sub_f32_e32 v19, 1.0, v253
	v_sub_f32_e32 v18, 1.0, v252
	v_pk_fma_f32 v[6:7], v[14:15], v[18:19], v[252:253]
	v_pk_fma_f32 v[4:5], v[12:13], v[16:17], v[250:251]
	global_store_dwordx4 v[8:9], v[4:7], off offset:-1472
